# prep gate pass: chunks>0 use a row loop without the padding-row mask; dot product on natural lr pairs; log fixups removed; scan: pipelined output reads, in-place state, k^T direct
# speedup vs baseline: 1.0095x; 1.0095x over previous
; #define LAS __attribute__((address_space(3)))
; __device__ __forceinline__ void gla_prep_phase(const Ctx& c, int j, LAS unsigned char* lds) {
;     ...
;         float up[16];
; #pragma unroll
;         for (int r = 0; r < 16; ++r) up[r] = pup[r];
;         const float bias = pbias;
;         { const int un = u + c.G; have = un < 2 * 16 * NCH; if (have) PREP_FETCH(un); }
;         __syncthreads();
;         float run = 0.f;
; #pragma unroll 4
;         for (int ii = 0; ii < 32; ++ii) { const int i = half * 32 + ii; float z = bias;
; #pragma unroll
;             for (int r = 0; r < 16; r += 4) { const f32x4 l4 = *(const LAS f32x4*)(LR + i * 16 + r); z += l4.x * up[r] + l4.y * up[r + 1] + l4.z * up[r + 2] + l4.w * up[r + 3]; }
;             const float ls = fminf(z, 0.f) - __logf(1.f + __expf(-fabsf(z)));
;             const bool valid = (ch > 0) || (i >= 48);
;             run += valid ? ls * (1.f / 16.f) : 0.f; CUM[i * 256 + d] = run; }
.LBB0_672:
	s_cmp_gt_i32 s12, 0
	s_mov_b32 s0, 0
	v_mov_b32_e32 v152, 0
	s_cselect_b64 s[96:97], -1, 0
	v_mov_b32_e32 v150, v135
	v_mov_b32_e32 v151, v134
	v_mov_b32_e32 v202, v2
	v_mov_b32_e32 v203, v0
	v_mov_b32_e32 v204, v4
	v_mov_b32_e32 v205, v6
	v_mov_b32_e32 v206, v3
	v_mov_b32_e32 v207, v1
	v_mov_b32_e32 v208, v5
	v_mov_b32_e32 v209, v7
	v_mov_b32_e32 v210, v10
	v_mov_b32_e32 v211, v8
	v_mov_b32_e32 v212, v12
	v_mov_b32_e32 v213, v14
	v_mov_b32_e32 v214, v11
	v_mov_b32_e32 v215, v9
	v_mov_b32_e32 v216, v13
	v_mov_b32_e32 v217, v15
	s_waitcnt lgkmcnt(0)
	s_barrier
	s_cmp_lg_u64 s[96:97], 0
	s_cbranch_scc1 .Lprep_fast_a
.LBB0_673:
	v_add_u32_e32 v173, 0, v150
	ds_read_b128 v[154:157], v173
	ds_read_b128 v[158:161], v173 offset:16
	ds_read_b128 v[162:165], v173 offset:32
	ds_read_b128 v[166:169], v173 offset:48
	v_add_u32_e32 v172, s0, v53
	v_add_u32_e32 v171, 0, v151
	v_add_u32_e32 v174, 2, v172
	s_add_i32 s0, s0, 4
	s_waitcnt lgkmcnt(0)
	v_pk_mul_f32 v[218:219], v[202:203], v[154:155]
	v_pk_mul_f32 v[220:221], v[210:211], v[162:163]
	v_pk_fma_f32 v[218:219], v[204:205], v[156:157], v[218:219]
	v_pk_fma_f32 v[220:221], v[212:213], v[164:165], v[220:221]
	v_pk_fma_f32 v[218:219], v[206:207], v[158:159], v[218:219]
	v_pk_fma_f32 v[220:221], v[214:215], v[166:167], v[220:221]
	v_pk_fma_f32 v[218:219], v[208:209], v[160:161], v[218:219]
	v_pk_fma_f32 v[220:221], v[216:217], v[168:169], v[220:221]
	s_nop 0
	v_pk_add_f32 v[218:219], v[218:219], v[220:221]
	s_nop 0
	v_add_f32_e32 v153, v105, v218
	v_add_f32_e32 v153, v153, v219
	v_min_f32_e32 v154, 0, v153
	v_mul_f32_e64 v153, |v153|, s6
	v_exp_f32_e32 v153, v153
	v_add_u32_e32 v151, 0x1000, v151
	v_add_u32_e32 v150, 0x100, v150
	v_add_f32_e32 v153, 1.0, v153
	v_log_f32_e32 v153, v153
	s_nop 0
	v_mul_f32_e32 v155, 0x3f317217, v153
	v_fma_f32 v155, v153, s8, -v155
	v_fmac_f32_e32 v155, 0x3377d1cf, v153
	v_fmac_f32_e32 v155, 0x3f317217, v153
	v_sub_f32_e32 v153, v154, v155
	v_cmp_lt_i32_e32 vcc, 47, v172
	s_or_b64 vcc, s[96:97], vcc
	v_mul_f32_e32 v153, 0x3d800000, v153
	v_cndmask_b32_e32 v153, 0, v153, vcc
	v_add_f32_e32 v170, v152, v153
	v_add_u32_e32 v152, 0x12000, v171
	ds_write_b32 v152, v170
	ds_read_b128 v[152:155], v173 offset:64
	ds_read_b128 v[156:159], v173 offset:80
	ds_read_b128 v[160:163], v173 offset:96
	ds_read_b128 v[164:167], v173 offset:112
	s_waitcnt lgkmcnt(0)
	v_pk_mul_f32 v[218:219], v[202:203], v[152:153]
	v_pk_mul_f32 v[220:221], v[210:211], v[160:161]
	v_pk_fma_f32 v[218:219], v[204:205], v[154:155], v[218:219]
	v_pk_fma_f32 v[220:221], v[212:213], v[162:163], v[220:221]
	v_pk_fma_f32 v[218:219], v[206:207], v[156:157], v[218:219]
	v_pk_fma_f32 v[220:221], v[214:215], v[164:165], v[220:221]
	v_pk_fma_f32 v[218:219], v[208:209], v[158:159], v[218:219]
	v_pk_fma_f32 v[220:221], v[216:217], v[166:167], v[220:221]
	s_nop 0
	v_pk_add_f32 v[218:219], v[218:219], v[220:221]
	s_nop 0
	v_add_f32_e32 v152, v105, v218
	v_add_f32_e32 v152, v152, v219
	v_min_f32_e32 v153, 0, v152
	v_mul_f32_e64 v152, |v152|, s6
	v_exp_f32_e32 v152, v152
	s_nop 0
	v_add_f32_e32 v152, 1.0, v152
	v_log_f32_e32 v152, v152
	s_nop 0
	v_mul_f32_e32 v154, 0x3f317217, v152
	v_fma_f32 v154, v152, s8, -v154
	v_fmac_f32_e32 v154, 0x3377d1cf, v152
	v_fmac_f32_e32 v154, 0x3f317217, v152
	v_sub_f32_e32 v152, v153, v154
	v_cmp_lt_i32_e32 vcc, 46, v172
	s_or_b64 vcc, s[96:97], vcc
	v_mul_f32_e32 v152, 0x3d800000, v152
	v_cndmask_b32_e32 v152, 0, v152, vcc
	v_add_f32_e32 v170, v170, v152
	v_add_u32_e32 v152, 0x12400, v171
	ds_write_b32 v152, v170
	ds_read_b128 v[152:155], v173 offset:128
	ds_read_b128 v[156:159], v173 offset:144
	ds_read_b128 v[160:163], v173 offset:160
	ds_read_b128 v[164:167], v173 offset:176
	v_add_u32_e32 v172, 3, v172
	s_waitcnt lgkmcnt(0)
	v_pk_mul_f32 v[218:219], v[202:203], v[152:153]
	v_pk_mul_f32 v[220:221], v[210:211], v[160:161]
	v_pk_fma_f32 v[218:219], v[204:205], v[154:155], v[218:219]
	v_pk_fma_f32 v[220:221], v[212:213], v[162:163], v[220:221]
	v_pk_fma_f32 v[218:219], v[206:207], v[156:157], v[218:219]
	v_pk_fma_f32 v[220:221], v[214:215], v[164:165], v[220:221]
	v_pk_fma_f32 v[218:219], v[208:209], v[158:159], v[218:219]
	v_pk_fma_f32 v[220:221], v[216:217], v[166:167], v[220:221]
	s_nop 0
	v_pk_add_f32 v[218:219], v[218:219], v[220:221]
	s_nop 0
	v_add_f32_e32 v152, v105, v218
	v_add_f32_e32 v152, v152, v219
	v_min_f32_e32 v153, 0, v152
	v_mul_f32_e64 v152, |v152|, s6
	v_exp_f32_e32 v152, v152
	s_nop 0
	v_add_f32_e32 v152, 1.0, v152
	v_log_f32_e32 v152, v152
	s_nop 0
	v_mul_f32_e32 v154, 0x3f317217, v152
	v_fma_f32 v154, v152, s8, -v154
	v_fmac_f32_e32 v154, 0x3377d1cf, v152
	v_fmac_f32_e32 v154, 0x3f317217, v152
	v_sub_f32_e32 v152, v153, v154
	v_cmp_lt_i32_e32 vcc, 47, v174
	s_or_b64 vcc, s[96:97], vcc
	v_mul_f32_e32 v152, 0x3d800000, v152
	v_cndmask_b32_e32 v152, 0, v152, vcc
	v_add_f32_e32 v170, v170, v152
	v_add_u32_e32 v152, 0x12800, v171
	ds_write_b32 v152, v170
	ds_read_b128 v[152:155], v173 offset:192
	ds_read_b128 v[156:159], v173 offset:208
	ds_read_b128 v[160:163], v173 offset:224
	ds_read_b128 v[164:167], v173 offset:240
	s_waitcnt lgkmcnt(0)
	v_pk_mul_f32 v[218:219], v[202:203], v[152:153]
	v_pk_mul_f32 v[220:221], v[210:211], v[160:161]
	v_pk_fma_f32 v[218:219], v[204:205], v[154:155], v[218:219]
	v_pk_fma_f32 v[220:221], v[212:213], v[162:163], v[220:221]
	v_pk_fma_f32 v[218:219], v[206:207], v[156:157], v[218:219]
	v_pk_fma_f32 v[220:221], v[214:215], v[164:165], v[220:221]
	v_pk_fma_f32 v[218:219], v[208:209], v[158:159], v[218:219]
	v_pk_fma_f32 v[220:221], v[216:217], v[166:167], v[220:221]
	s_nop 0
	v_pk_add_f32 v[218:219], v[218:219], v[220:221]
	s_nop 0
	v_add_f32_e32 v152, v105, v218
	v_add_f32_e32 v152, v152, v219
	v_min_f32_e32 v153, 0, v152
	v_mul_f32_e64 v152, |v152|, s6
	v_exp_f32_e32 v152, v152
	s_nop 0
	v_add_f32_e32 v152, 1.0, v152
	v_log_f32_e32 v152, v152
	s_nop 0
	v_mul_f32_e32 v154, 0x3f317217, v152
	v_fma_f32 v154, v152, s8, -v154
	v_fmac_f32_e32 v154, 0x3377d1cf, v152
	v_fmac_f32_e32 v154, 0x3f317217, v152
	v_sub_f32_e32 v152, v153, v154
	v_cmp_lt_i32_e32 vcc, 47, v172
	s_or_b64 vcc, s[96:97], vcc
	v_mul_f32_e32 v152, 0x3d800000, v152
	v_cndmask_b32_e32 v152, 0, v152, vcc
	v_add_f32_e32 v152, v170, v152
	v_add_u32_e32 v153, 0x12c00, v171
	s_cmp_eq_u32 s0, 32
	ds_write_b32 v153, v152
	s_cbranch_scc0 .LBB0_673
	s_branch .Lprep_join_a
; #define LAS __attribute__((address_space(3)))
; __device__ __forceinline__ void gla_prep_phase(const Ctx& c, int j, LAS unsigned char* lds) {
;     ...
;         for (int ii = 0; ii < 32; ++ii) { const int i = half * 32 + ii; float z = bias;
; #pragma unroll
;             for (int r = 0; r < 16; r += 4) { const f32x4 l4 = *(const LAS f32x4*)(LR + i * 16 + r); z += l4.x * up[r] + l4.y * up[r + 1] + l4.z * up[r + 2] + l4.w * up[r + 3]; }
;             const float ls = fminf(z, 0.f) - __logf(1.f + __expf(-fabsf(z)));
;             const bool valid = (ch > 0) || (i >= 48);
;             run += valid ? ls * (1.f / 16.f) : 0.f; CUM[i * 256 + d] = run; }
.Lprep_fast_a:
	v_add_u32_e32 v173, 0, v150
	ds_read_b128 v[154:157], v173
	ds_read_b128 v[158:161], v173 offset:16
	ds_read_b128 v[162:165], v173 offset:32
	ds_read_b128 v[166:169], v173 offset:48
	v_add_u32_e32 v171, 0, v151
	s_add_i32 s0, s0, 4
	s_waitcnt lgkmcnt(0)
	v_pk_mul_f32 v[218:219], v[202:203], v[154:155]
	v_pk_mul_f32 v[220:221], v[210:211], v[162:163]
	v_pk_fma_f32 v[218:219], v[204:205], v[156:157], v[218:219]
	v_pk_fma_f32 v[220:221], v[212:213], v[164:165], v[220:221]
	v_pk_fma_f32 v[218:219], v[206:207], v[158:159], v[218:219]
	v_pk_fma_f32 v[220:221], v[214:215], v[166:167], v[220:221]
	v_pk_fma_f32 v[218:219], v[208:209], v[160:161], v[218:219]
	v_pk_fma_f32 v[220:221], v[216:217], v[168:169], v[220:221]
	s_nop 0
	v_pk_add_f32 v[218:219], v[218:219], v[220:221]
	s_nop 0
	v_add_f32_e32 v153, v105, v218
	v_add_f32_e32 v153, v153, v219
	v_min_f32_e32 v154, 0, v153
	v_mul_f32_e64 v153, |v153|, s6
	v_exp_f32_e32 v153, v153
	v_add_u32_e32 v151, 0x1000, v151
	v_add_u32_e32 v150, 0x100, v150
	v_add_f32_e32 v153, 1.0, v153
	v_log_f32_e32 v153, v153
	s_nop 0
	v_mul_f32_e32 v155, 0x3f317217, v153
	v_fma_f32 v155, v153, s8, -v155
	v_fmac_f32_e32 v155, 0x3377d1cf, v153
	v_fmac_f32_e32 v155, 0x3f317217, v153
	v_sub_f32_e32 v153, v154, v155
	v_mul_f32_e32 v153, 0x3d800000, v153
	v_add_f32_e32 v170, v152, v153
	v_add_u32_e32 v152, 0x12000, v171
	ds_write_b32 v152, v170
	ds_read_b128 v[152:155], v173 offset:64
	ds_read_b128 v[156:159], v173 offset:80
	ds_read_b128 v[160:163], v173 offset:96
	ds_read_b128 v[164:167], v173 offset:112
	s_waitcnt lgkmcnt(0)
	v_pk_mul_f32 v[218:219], v[202:203], v[152:153]
	v_pk_mul_f32 v[220:221], v[210:211], v[160:161]
	v_pk_fma_f32 v[218:219], v[204:205], v[154:155], v[218:219]
	v_pk_fma_f32 v[220:221], v[212:213], v[162:163], v[220:221]
	v_pk_fma_f32 v[218:219], v[206:207], v[156:157], v[218:219]
	v_pk_fma_f32 v[220:221], v[214:215], v[164:165], v[220:221]
	v_pk_fma_f32 v[218:219], v[208:209], v[158:159], v[218:219]
	v_pk_fma_f32 v[220:221], v[216:217], v[166:167], v[220:221]
	s_nop 0
	v_pk_add_f32 v[218:219], v[218:219], v[220:221]
	s_nop 0
	v_add_f32_e32 v152, v105, v218
	v_add_f32_e32 v152, v152, v219
	v_min_f32_e32 v153, 0, v152
	v_mul_f32_e64 v152, |v152|, s6
	v_exp_f32_e32 v152, v152
	s_nop 0
	v_add_f32_e32 v152, 1.0, v152
	v_log_f32_e32 v152, v152
	s_nop 0
	v_mul_f32_e32 v154, 0x3f317217, v152
	v_fma_f32 v154, v152, s8, -v154
	v_fmac_f32_e32 v154, 0x3377d1cf, v152
	v_fmac_f32_e32 v154, 0x3f317217, v152
	v_sub_f32_e32 v152, v153, v154
	v_mul_f32_e32 v152, 0x3d800000, v152
	v_add_f32_e32 v170, v170, v152
	v_add_u32_e32 v152, 0x12400, v171
	ds_write_b32 v152, v170
	ds_read_b128 v[152:155], v173 offset:128
	ds_read_b128 v[156:159], v173 offset:144
	ds_read_b128 v[160:163], v173 offset:160
	ds_read_b128 v[164:167], v173 offset:176
	s_waitcnt lgkmcnt(0)
	v_pk_mul_f32 v[218:219], v[202:203], v[152:153]
	v_pk_mul_f32 v[220:221], v[210:211], v[160:161]
	v_pk_fma_f32 v[218:219], v[204:205], v[154:155], v[218:219]
	v_pk_fma_f32 v[220:221], v[212:213], v[162:163], v[220:221]
	v_pk_fma_f32 v[218:219], v[206:207], v[156:157], v[218:219]
	v_pk_fma_f32 v[220:221], v[214:215], v[164:165], v[220:221]
	v_pk_fma_f32 v[218:219], v[208:209], v[158:159], v[218:219]
	v_pk_fma_f32 v[220:221], v[216:217], v[166:167], v[220:221]
	s_nop 0
	v_pk_add_f32 v[218:219], v[218:219], v[220:221]
	s_nop 0
	v_add_f32_e32 v152, v105, v218
	v_add_f32_e32 v152, v152, v219
	v_min_f32_e32 v153, 0, v152
	v_mul_f32_e64 v152, |v152|, s6
	v_exp_f32_e32 v152, v152
	s_nop 0
	v_add_f32_e32 v152, 1.0, v152
	v_log_f32_e32 v152, v152
	s_nop 0
	v_mul_f32_e32 v154, 0x3f317217, v152
	v_fma_f32 v154, v152, s8, -v154
	v_fmac_f32_e32 v154, 0x3377d1cf, v152
	v_fmac_f32_e32 v154, 0x3f317217, v152
	v_sub_f32_e32 v152, v153, v154
	v_mul_f32_e32 v152, 0x3d800000, v152
	v_add_f32_e32 v170, v170, v152
	v_add_u32_e32 v152, 0x12800, v171
	ds_write_b32 v152, v170
	ds_read_b128 v[152:155], v173 offset:192
	ds_read_b128 v[156:159], v173 offset:208
	ds_read_b128 v[160:163], v173 offset:224
	ds_read_b128 v[164:167], v173 offset:240
	s_waitcnt lgkmcnt(0)
	v_pk_mul_f32 v[218:219], v[202:203], v[152:153]
	v_pk_mul_f32 v[220:221], v[210:211], v[160:161]
	v_pk_fma_f32 v[218:219], v[204:205], v[154:155], v[218:219]
	v_pk_fma_f32 v[220:221], v[212:213], v[162:163], v[220:221]
	v_pk_fma_f32 v[218:219], v[206:207], v[156:157], v[218:219]
	v_pk_fma_f32 v[220:221], v[214:215], v[164:165], v[220:221]
	v_pk_fma_f32 v[218:219], v[208:209], v[158:159], v[218:219]
	v_pk_fma_f32 v[220:221], v[216:217], v[166:167], v[220:221]
	s_nop 0
	v_pk_add_f32 v[218:219], v[218:219], v[220:221]
	s_nop 0
	v_add_f32_e32 v152, v105, v218
	v_add_f32_e32 v152, v152, v219
	v_min_f32_e32 v153, 0, v152
	v_mul_f32_e64 v152, |v152|, s6
	v_exp_f32_e32 v152, v152
	s_nop 0
	v_add_f32_e32 v152, 1.0, v152
	v_log_f32_e32 v152, v152
	s_nop 0
	v_mul_f32_e32 v154, 0x3f317217, v152
	v_fma_f32 v154, v152, s8, -v154
	v_fmac_f32_e32 v154, 0x3377d1cf, v152
	v_fmac_f32_e32 v154, 0x3f317217, v152
	v_sub_f32_e32 v152, v153, v154
	v_mul_f32_e32 v152, 0x3d800000, v152
	v_add_f32_e32 v152, v170, v152
	v_add_u32_e32 v153, 0x12c00, v171
	s_cmp_eq_u32 s0, 32
	ds_write_b32 v153, v152
	s_cbranch_scc0 .Lprep_fast_a
; __device__ __forceinline__ unsigned cvt_pk_bf16(float lo, float hi) { unsigned r; asm volatile("v_cvt_pk_bf16_f32 %0, %1, %2" : "=v"(r) : "v"(lo), "v"(hi)); return r; }
; #define LAS __attribute__((address_space(3)))
; __device__ __forceinline__ void gla_prep_phase(const Ctx& c, int j, LAS unsigned char* lds) {
;     ...
;         TOT[half * 256 + d] = run;
;         __syncthreads();
;         const size_t tile = (size_t)(dir * 16 + bh) * NCH + ch;
;         bf16_t* qdst = QD + tile * (64 * 256);
;         {
;             const int dq = (c.tid & 63) * 4, i0 = (c.tid >> 6) * 8, hf = i0 >> 5;
;             const f32x4 t0 = *(const LAS f32x4*)(TOT + dq), t1 = *(const LAS f32x4*)(TOT + 256 + dq), total = t0 + t1;
;             const f32x4 off0 = hf ? t0 : (f32x4){0.f, 0.f, 0.f, 0.f}, sbase = hf ? t1 : total;
;             f32x4 etot; etot.x = __expf(total.x); etot.y = __expf(total.y); etot.z = __expf(total.z); etot.w = __expf(total.w);
;             f32x4 prev = (i0 & 31) ? *(const LAS f32x4*)(CUM + (i0 - 1) * 256 + dq) : (f32x4){0.f, 0.f, 0.f, 0.f};
;             float kf[4][8];
; #pragma unroll
;             for (int e = 0; e < 8; ++e) { const int i = i0 + e;
;                 const f32x4 incl = *(const LAS f32x4*)(CUM + i * 256 + dq);
;                 const f32x4 cum = (dir == 0) ? (off0 + incl) : (sbase - prev); prev = incl;
;                 const u32x2 qw = *(const LAS u32x2*)(QL + i * 528 + dq * 2), kw = *(const LAS u32x2*)(KL + i * 528 + dq * 2);
;                 const float qv[4] = {__uint_as_float(qw.x << 16), __uint_as_float(qw.x & 0xffff0000u), __uint_as_float(qw.y << 16), __uint_as_float(qw.y & 0xffff0000u)};
;                 const float kv[4] = {__uint_as_float(kw.x << 16), __uint_as_float(kw.x & 0xffff0000u), __uint_as_float(kw.y << 16), __uint_as_float(kw.y & 0xffff0000u)};
;                 float qd[4], ki[4];
; #pragma unroll
;                 for (int jx = 0; jx < 4; ++jx) { const float ec = __expf(cum[jx]), rc = __builtin_amdgcn_rcpf(ec);
;                     qd[jx] = qv[jx] * ec * (1.f / 16.f); ki[jx] = kv[jx] * rc; kf[jx][e] = ki[jx] * etot[jx]; }
;                 *(LAS u32x2*)(QL + i * 528 + dq * 2) = (u32x2){pg8::cvt_pk_bf16(qd[0], qd[1]), pg8::cvt_pk_bf16(qd[2], qd[3])};
;                 *(LAS u32x2*)(KL + i * 528 + dq * 2) = (u32x2){pg8::cvt_pk_bf16(ki[0], ki[1]), pg8::cvt_pk_bf16(ki[2], ki[3])}; }
.Lprep_join_a:
	ds_write_b32 v91, v152 offset:4096
	s_waitcnt lgkmcnt(0)
	s_barrier
	ds_read_b128 v[0:3], v128 offset:4096
	ds_read_b128 v[8:11], v128 offset:5120
	v_mov_b32_e32 v4, 0
	v_mov_b32_e32 v5, 0
	v_mov_b32_e32 v6, 0
	v_mov_b32_e32 v7, 0
	s_and_saveexec_b64 s[0:1], s[38:39]
	ds_read_b128 v[4:7], v132
	s_or_b64 exec, exec, s[0:1]
	s_waitcnt lgkmcnt(0)
	v_pk_add_f32 v[150:151], v[0:1], v[8:9]
	s_lshl_b32 s0, s94, 4
	v_pk_add_f32 v[154:155], v[2:3], v[10:11]
	v_cndmask_b32_e64 v14, v9, v151, s[36:37]
	v_cndmask_b32_e64 v9, v3, 0, s[36:37]
	v_add_u32_e32 v3, v130, v129
	s_add_i32 s0, s0, s13
	v_cndmask_b32_e64 v12, v11, v155, s[36:37]
	v_cndmask_b32_e64 v13, v10, v154, s[36:37]
	v_cndmask_b32_e64 v15, v8, v150, s[36:37]
	v_cndmask_b32_e64 v11, v1, 0, s[36:37]
	v_cndmask_b32_e64 v10, v0, 0, s[36:37]
	v_mul_f32_e32 v0, 0x3fb8aa3b, v150
	v_mul_f32_e32 v1, 0x3fb8aa3b, v151
	ds_read_b128 v[150:153], v3
	s_mul_hi_i32 s1, s0, 0x41
	s_mulk_i32 s0, 0x41
	s_ashr_i32 s13, s12, 31
	s_add_u32 s94, s0, s12
	s_addc_u32 s95, s1, s13
	s_add_i32 s0, s11, 0x40f
	s_cmpk_lt_u32 s0, 0x81f
	v_cndmask_b32_e64 v8, v2, 0, s[36:37]
	v_mul_f32_e32 v2, 0x3fb8aa3b, v154
	v_mul_f32_e32 v3, 0x3fb8aa3b, v155
	s_waitcnt lgkmcnt(0)
	v_pk_add_f32 v[154:155], v[10:11], v[150:151]
	v_sub_f32_e32 v159, v15, v4
	v_sub_f32_e32 v160, v14, v5
	s_cselect_b64 s[54:55], -1, 0
	v_sub_f32_e32 v105, v13, v6
	v_sub_f32_e32 v158, v12, v7
	ds_read2st64_b64 v[4:7], v138 offset0:12 offset1:78
	v_cndmask_b32_e64 v155, v160, v155, s[54:55]
	v_cndmask_b32_e64 v154, v159, v154, s[54:55]
	v_mul_f32_e32 v154, 0x3fb8aa3b, v154
	v_mul_f32_e32 v155, 0x3fb8aa3b, v155
	v_exp_f32_e32 v154, v154
	v_exp_f32_e32 v155, v155
	v_pk_add_f32 v[156:157], v[8:9], v[152:153]
	s_waitcnt lgkmcnt(0)
	v_lshlrev_b32_e32 v159, 16, v6
	v_cndmask_b32_e64 v157, v158, v157, s[54:55]
	v_cndmask_b32_e64 v105, v105, v156, s[54:55]
	v_lshlrev_b32_e32 v156, 16, v4
	v_and_b32_e32 v4, 0xffff0000, v4
	v_rcp_f32_e32 v161, v154
	v_mul_f32_e32 v154, v154, v156
	v_rcp_f32_e32 v156, v155
	v_mul_f32_e32 v4, v155, v4
	v_mul_f32_e32 v105, 0x3fb8aa3b, v105
	v_mul_f32_e32 v155, 0x3fb8aa3b, v157
	v_exp_f32_e32 v105, v105
	v_exp_f32_e32 v155, v155
	v_and_b32_e32 v6, 0xffff0000, v6
	v_lshlrev_b32_e32 v158, 16, v5
	v_and_b32_e32 v5, 0xffff0000, v5
	v_mul_f32_e32 v6, v156, v6
	v_rcp_f32_e32 v156, v105
	v_rcp_f32_e32 v157, v155
	v_mul_f32_e32 v5, v155, v5
	v_mul_f32_e32 v4, 0x3d800000, v4
	v_mul_f32_e32 v105, v105, v158
	v_mul_f32_e32 v5, 0x3d800000, v5
	v_lshlrev_b32_e32 v160, 16, v7
	v_and_b32_e32 v7, 0xffff0000, v7
	v_mul_f32_e32 v154, 0x3d800000, v154
	v_mul_f32_e32 v105, 0x3d800000, v105
	v_cvt_pk_bf16_f32 v4, v154, v4
	v_cvt_pk_bf16_f32 v5, v105, v5
	v_mul_f32_e32 v159, v161, v159
	v_mul_f32_e32 v158, v156, v160
	v_mul_f32_e32 v160, v157, v7
	ds_write_b64 v138, v[4:5] offset:6144
	v_cvt_pk_bf16_f32 v4, v159, v6
	v_cvt_pk_bf16_f32 v5, v158, v160
	ds_write_b64 v138, v[4:5] offset:39936
	ds_read_b128 v[154:157], v139
	v_exp_f32_e32 v0, v0
	v_exp_f32_e32 v2, v2
	v_sub_f32_e32 v105, v15, v150
	v_sub_f32_e32 v162, v14, v151
	v_mul_f32_e32 v7, v0, v159
	v_mul_f32_e32 v5, v2, v158
	s_waitcnt lgkmcnt(0)
	v_pk_add_f32 v[158:159], v[10:11], v[154:155]
	v_add_u32_e32 v150, 16, v138
	v_cndmask_b32_e64 v105, v105, v158, s[54:55]
	v_mul_f32_e32 v105, 0x3fb8aa3b, v105
	v_exp_f32_e32 v105, v105
	v_exp_f32_e32 v3, v3
	v_sub_f32_e32 v163, v13, v152
	v_sub_f32_e32 v164, v12, v153
	ds_read2st64_b64 v[150:153], v150 offset0:13 offset1:79
	v_cndmask_b32_e64 v159, v162, v159, s[54:55]
	v_mul_f32_e32 v159, 0x3fb8aa3b, v159
	v_rcp_f32_e32 v165, v105
	v_exp_f32_e32 v159, v159
	v_mul_f32_e32 v4, v3, v160
	v_pk_add_f32 v[160:161], v[8:9], v[156:157]
	s_waitcnt lgkmcnt(0)
	v_lshlrev_b32_e32 v158, 16, v150
	v_cndmask_b32_e64 v160, v163, v160, s[54:55]
	v_lshlrev_b32_e32 v163, 16, v152
	v_mul_f32_e32 v105, v105, v158
	v_mul_f32_e32 v158, v165, v163
	v_rcp_f32_e32 v163, v159
	v_cndmask_b32_e64 v161, v164, v161, s[54:55]
	v_and_b32_e32 v150, 0xffff0000, v150
	v_and_b32_e32 v152, 0xffff0000, v152
	v_mul_f32_e32 v150, v159, v150
	v_mul_f32_e32 v159, 0x3fb8aa3b, v160
	v_mul_f32_e32 v160, v163, v152
	v_mul_f32_e32 v152, 0x3fb8aa3b, v161
	v_exp_f32_e32 v159, v159
	v_exp_f32_e32 v152, v152
	v_lshlrev_b32_e32 v162, 16, v151
	v_and_b32_e32 v151, 0xffff0000, v151
	v_rcp_f32_e32 v161, v159
	v_mul_f32_e32 v159, v159, v162
	v_rcp_f32_e32 v162, v152
	v_mul_f32_e32 v151, v152, v151
	v_mul_f32_e32 v150, 0x3d800000, v150
	v_mul_f32_e32 v151, 0x3d800000, v151
	v_lshlrev_b32_e32 v164, 16, v153
	v_and_b32_e32 v153, 0xffff0000, v153
	v_mul_f32_e32 v105, 0x3d800000, v105
	v_mul_f32_e32 v159, 0x3d800000, v159
	v_cvt_pk_bf16_f32 v150, v105, v150
	v_cvt_pk_bf16_f32 v151, v159, v151
	v_mul_f32_e32 v161, v161, v164
	v_mul_f32_e32 v162, v162, v153
	ds_write_b64 v138, v[150:151] offset:6672
	v_cvt_pk_bf16_f32 v150, v158, v160
	v_cvt_pk_bf16_f32 v151, v161, v162
	ds_write_b64 v138, v[150:151] offset:40464
	ds_read_b128 v[150:153], v140
	v_mul_f32_e32 v163, v0, v158
	v_mul_f32_e32 v105, v3, v162
	v_sub_f32_e32 v162, v15, v154
	v_sub_f32_e32 v166, v14, v155
	s_waitcnt lgkmcnt(0)
	v_pk_add_f32 v[158:159], v[10:11], v[150:151]
	v_add_u32_e32 v154, 32, v138
	v_cndmask_b32_e64 v158, v162, v158, s[54:55]
	v_mul_f32_e32 v158, 0x3fb8aa3b, v158
	v_exp_f32_e32 v158, v158
	v_exp_f32_e32 v1, v1
	v_sub_f32_e32 v167, v13, v156
	v_sub_f32_e32 v168, v12, v157
	ds_read2st64_b64 v[154:157], v154 offset0:14 offset1:80
	v_cndmask_b32_e64 v159, v166, v159, s[54:55]
	v_mul_f32_e32 v159, 0x3fb8aa3b, v159
	v_rcp_f32_e32 v169, v158
	v_exp_f32_e32 v159, v159
	v_mul_f32_e32 v164, v1, v160
	v_mul_f32_e32 v165, v2, v161
	v_pk_add_f32 v[160:161], v[8:9], v[152:153]
	s_waitcnt lgkmcnt(0)
; __device__ __forceinline__ unsigned cvt_pk_bf16(float lo, float hi) { unsigned r; asm volatile("v_cvt_pk_bf16_f32 %0, %1, %2" : "=v"(r) : "v"(lo), "v"(hi)); return r; }
; #define LAS __attribute__((address_space(3)))
; __device__ __forceinline__ void gla_prep_phase(const Ctx& c, int j, LAS unsigned char* lds) {
;     ...
;             for (int e = 0; e < 8; ++e) { const int i = i0 + e;
;                 const f32x4 incl = *(const LAS f32x4*)(CUM + i * 256 + dq);
;                 const f32x4 cum = (dir == 0) ? (off0 + incl) : (sbase - prev); prev = incl;
;                 const u32x2 qw = *(const LAS u32x2*)(QL + i * 528 + dq * 2), kw = *(const LAS u32x2*)(KL + i * 528 + dq * 2);
;                 const float qv[4] = {__uint_as_float(qw.x << 16), __uint_as_float(qw.x & 0xffff0000u), __uint_as_float(qw.y << 16), __uint_as_float(qw.y & 0xffff0000u)};
;                 const float kv[4] = {__uint_as_float(kw.x << 16), __uint_as_float(kw.x & 0xffff0000u), __uint_as_float(kw.y << 16), __uint_as_float(kw.y & 0xffff0000u)};
;                 float qd[4], ki[4];
; #pragma unroll
;                 for (int jx = 0; jx < 4; ++jx) { const float ec = __expf(cum[jx]), rc = __builtin_amdgcn_rcpf(ec);
;                     qd[jx] = qv[jx] * ec * (1.f / 16.f); ki[jx] = kv[jx] * rc; kf[jx][e] = ki[jx] * etot[jx]; }
;                 *(LAS u32x2*)(QL + i * 528 + dq * 2) = (u32x2){pg8::cvt_pk_bf16(qd[0], qd[1]), pg8::cvt_pk_bf16(qd[2], qd[3])};
;                 *(LAS u32x2*)(KL + i * 528 + dq * 2) = (u32x2){pg8::cvt_pk_bf16(ki[0], ki[1]), pg8::cvt_pk_bf16(ki[2], ki[3])}; }
	v_lshlrev_b32_e32 v162, 16, v154
	v_cndmask_b32_e64 v160, v167, v160, s[54:55]
	v_lshlrev_b32_e32 v167, 16, v156
	v_mul_f32_e32 v158, v158, v162
	v_mul_f32_e32 v162, v169, v167
	v_rcp_f32_e32 v167, v159
	v_cndmask_b32_e64 v161, v168, v161, s[54:55]
	v_and_b32_e32 v154, 0xffff0000, v154
	v_and_b32_e32 v156, 0xffff0000, v156
	v_mul_f32_e32 v154, v159, v154
	v_mul_f32_e32 v159, 0x3fb8aa3b, v160
	v_mul_f32_e32 v160, v167, v156
	v_mul_f32_e32 v156, 0x3fb8aa3b, v161
	v_exp_f32_e32 v159, v159
	v_exp_f32_e32 v156, v156
	v_lshlrev_b32_e32 v166, 16, v155
	v_and_b32_e32 v155, 0xffff0000, v155
	v_rcp_f32_e32 v161, v159
	v_mul_f32_e32 v159, v159, v166
	v_rcp_f32_e32 v166, v156
	v_mul_f32_e32 v155, v156, v155
	v_mul_f32_e32 v154, 0x3d800000, v154
	v_mul_f32_e32 v155, 0x3d800000, v155
	v_lshlrev_b32_e32 v168, 16, v157
	v_and_b32_e32 v157, 0xffff0000, v157
	v_mul_f32_e32 v158, 0x3d800000, v158
	v_mul_f32_e32 v159, 0x3d800000, v159
	v_cvt_pk_bf16_f32 v154, v158, v154
	v_cvt_pk_bf16_f32 v155, v159, v155
	v_mul_f32_e32 v161, v161, v168
	v_mul_f32_e32 v166, v166, v157
	ds_write_b64 v138, v[154:155] offset:7200
	v_cvt_pk_bf16_f32 v154, v162, v160
	v_cvt_pk_bf16_f32 v155, v161, v166
	ds_write_b64 v138, v[154:155] offset:40992
	ds_read_b128 v[154:157], v141
	v_sub_f32_e32 v169, v15, v150
	v_sub_f32_e32 v170, v14, v151
	v_add_u32_e32 v150, 48, v138
	v_sub_f32_e32 v171, v13, v152
	s_waitcnt lgkmcnt(0)
	v_pk_add_f32 v[158:159], v[10:11], v[154:155]
	v_sub_f32_e32 v172, v12, v153
	v_cndmask_b32_e64 v158, v169, v158, s[54:55]
	v_mul_f32_e32 v158, 0x3fb8aa3b, v158
	v_exp_f32_e32 v158, v158
	ds_read2st64_b64 v[150:153], v150 offset0:15 offset1:81
	v_cndmask_b32_e64 v159, v170, v159, s[54:55]
	v_mul_f32_e32 v159, 0x3fb8aa3b, v159
	v_rcp_f32_e32 v173, v158
	v_exp_f32_e32 v159, v159
	v_mul_f32_e32 v167, v1, v160
	v_mul_f32_e32 v168, v2, v161
	v_pk_add_f32 v[160:161], v[8:9], v[156:157]
	s_waitcnt lgkmcnt(0)
	v_lshlrev_b32_e32 v169, 16, v150
	v_cndmask_b32_e64 v160, v171, v160, s[54:55]
	v_lshlrev_b32_e32 v171, 16, v152
	v_mul_f32_e32 v158, v158, v169
	v_mul_f32_e32 v169, v173, v171
	v_rcp_f32_e32 v171, v159
	v_cndmask_b32_e64 v161, v172, v161, s[54:55]
	v_and_b32_e32 v150, 0xffff0000, v150
	v_and_b32_e32 v152, 0xffff0000, v152
	v_mul_f32_e32 v150, v159, v150
	v_mul_f32_e32 v159, 0x3fb8aa3b, v160
	v_mul_f32_e32 v160, v171, v152
	v_mul_f32_e32 v152, 0x3fb8aa3b, v161
	v_exp_f32_e32 v159, v159
	v_exp_f32_e32 v152, v152
	v_lshlrev_b32_e32 v170, 16, v151
	v_and_b32_e32 v151, 0xffff0000, v151
	v_rcp_f32_e32 v161, v159
	v_mul_f32_e32 v159, v159, v170
	v_rcp_f32_e32 v170, v152
	v_mul_f32_e32 v151, v152, v151
	v_mul_f32_e32 v150, 0x3d800000, v150
	v_mul_f32_e32 v151, 0x3d800000, v151
	v_lshlrev_b32_e32 v172, 16, v153
	v_and_b32_e32 v153, 0xffff0000, v153
	v_mul_f32_e32 v158, 0x3d800000, v158
	v_mul_f32_e32 v159, 0x3d800000, v159
	v_cvt_pk_bf16_f32 v150, v158, v150
	v_cvt_pk_bf16_f32 v151, v159, v151
	v_mul_f32_e32 v161, v161, v172
	v_mul_f32_e32 v170, v170, v153
	ds_write_b64 v138, v[150:151] offset:7728
	v_cvt_pk_bf16_f32 v150, v169, v160
	v_cvt_pk_bf16_f32 v151, v161, v170
	ds_write_b64 v138, v[150:151] offset:41520
	ds_read_b128 v[150:153], v142
	v_sub_f32_e32 v173, v15, v154
	v_sub_f32_e32 v174, v14, v155
	v_add_u32_e32 v154, 64, v138
	v_sub_f32_e32 v175, v13, v156
	s_waitcnt lgkmcnt(0)
	v_pk_add_f32 v[158:159], v[10:11], v[150:151]
	v_sub_f32_e32 v176, v12, v157
	v_cndmask_b32_e64 v158, v173, v158, s[54:55]
	v_mul_f32_e32 v158, 0x3fb8aa3b, v158
	v_exp_f32_e32 v158, v158
	ds_read2st64_b64 v[154:157], v154 offset0:16 offset1:82
	v_cndmask_b32_e64 v159, v174, v159, s[54:55]
	v_mul_f32_e32 v159, 0x3fb8aa3b, v159
	v_rcp_f32_e32 v177, v158
	v_exp_f32_e32 v159, v159
	v_mul_f32_e32 v171, v1, v160
	v_mul_f32_e32 v172, v2, v161
	v_pk_add_f32 v[160:161], v[8:9], v[152:153]
	s_waitcnt lgkmcnt(0)
	v_lshlrev_b32_e32 v173, 16, v154
	v_cndmask_b32_e64 v160, v175, v160, s[54:55]
	v_lshlrev_b32_e32 v175, 16, v156
	v_mul_f32_e32 v158, v158, v173
	v_mul_f32_e32 v173, v177, v175
	v_rcp_f32_e32 v175, v159
	v_cndmask_b32_e64 v161, v176, v161, s[54:55]
	v_and_b32_e32 v154, 0xffff0000, v154
	v_and_b32_e32 v156, 0xffff0000, v156
	v_mul_f32_e32 v154, v159, v154
	v_mul_f32_e32 v159, 0x3fb8aa3b, v160
	v_mul_f32_e32 v160, v175, v156
	v_mul_f32_e32 v156, 0x3fb8aa3b, v161
	v_exp_f32_e32 v159, v159
	v_exp_f32_e32 v156, v156
	v_lshlrev_b32_e32 v174, 16, v155
	v_and_b32_e32 v155, 0xffff0000, v155
	v_rcp_f32_e32 v161, v159
	v_mul_f32_e32 v159, v159, v174
	v_rcp_f32_e32 v174, v156
	v_mul_f32_e32 v155, v156, v155
	v_mul_f32_e32 v154, 0x3d800000, v154
	v_mul_f32_e32 v155, 0x3d800000, v155
	v_lshlrev_b32_e32 v176, 16, v157
	v_and_b32_e32 v157, 0xffff0000, v157
	v_mul_f32_e32 v158, 0x3d800000, v158
	v_mul_f32_e32 v159, 0x3d800000, v159
	v_cvt_pk_bf16_f32 v154, v158, v154
	v_cvt_pk_bf16_f32 v155, v159, v155
	v_mul_f32_e32 v161, v161, v176
	v_mul_f32_e32 v174, v174, v157
	ds_write_b64 v138, v[154:155] offset:8256
	v_cvt_pk_bf16_f32 v154, v173, v160
	v_cvt_pk_bf16_f32 v155, v161, v174
	ds_write_b64 v138, v[154:155] offset:42048
	ds_read_b128 v[154:157], v143
	v_sub_f32_e32 v177, v15, v150
	v_sub_f32_e32 v178, v14, v151
	v_add_u32_e32 v150, 0x50, v138
	v_sub_f32_e32 v179, v13, v152
	s_waitcnt lgkmcnt(0)
	v_pk_add_f32 v[158:159], v[10:11], v[154:155]
	v_sub_f32_e32 v180, v12, v153
	v_cndmask_b32_e64 v158, v177, v158, s[54:55]
	v_mul_f32_e32 v158, 0x3fb8aa3b, v158
	v_exp_f32_e32 v158, v158
	ds_read2st64_b64 v[150:153], v150 offset0:17 offset1:83
	v_cndmask_b32_e64 v159, v178, v159, s[54:55]
	v_mul_f32_e32 v159, 0x3fb8aa3b, v159
	v_rcp_f32_e32 v181, v158
	v_exp_f32_e32 v159, v159
	v_mul_f32_e32 v175, v1, v160
	v_mul_f32_e32 v176, v2, v161
	v_pk_add_f32 v[160:161], v[8:9], v[156:157]
	s_waitcnt lgkmcnt(0)
; __device__ __forceinline__ unsigned cvt_pk_bf16(float lo, float hi) { unsigned r; asm volatile("v_cvt_pk_bf16_f32 %0, %1, %2" : "=v"(r) : "v"(lo), "v"(hi)); return r; }
; #define LAS __attribute__((address_space(3)))
; __device__ __forceinline__ void gla_prep_phase(const Ctx& c, int j, LAS unsigned char* lds) {
;     ...
;             for (int e = 0; e < 8; ++e) { const int i = i0 + e;
;                 const f32x4 incl = *(const LAS f32x4*)(CUM + i * 256 + dq);
;                 const f32x4 cum = (dir == 0) ? (off0 + incl) : (sbase - prev); prev = incl;
;                 const u32x2 qw = *(const LAS u32x2*)(QL + i * 528 + dq * 2), kw = *(const LAS u32x2*)(KL + i * 528 + dq * 2);
;                 const float qv[4] = {__uint_as_float(qw.x << 16), __uint_as_float(qw.x & 0xffff0000u), __uint_as_float(qw.y << 16), __uint_as_float(qw.y & 0xffff0000u)};
;                 const float kv[4] = {__uint_as_float(kw.x << 16), __uint_as_float(kw.x & 0xffff0000u), __uint_as_float(kw.y << 16), __uint_as_float(kw.y & 0xffff0000u)};
;                 float qd[4], ki[4];
; #pragma unroll
;                 for (int jx = 0; jx < 4; ++jx) { const float ec = __expf(cum[jx]), rc = __builtin_amdgcn_rcpf(ec);
;                     qd[jx] = qv[jx] * ec * (1.f / 16.f); ki[jx] = kv[jx] * rc; kf[jx][e] = ki[jx] * etot[jx]; }
;                 *(LAS u32x2*)(QL + i * 528 + dq * 2) = (u32x2){pg8::cvt_pk_bf16(qd[0], qd[1]), pg8::cvt_pk_bf16(qd[2], qd[3])};
;                 *(LAS u32x2*)(KL + i * 528 + dq * 2) = (u32x2){pg8::cvt_pk_bf16(ki[0], ki[1]), pg8::cvt_pk_bf16(ki[2], ki[3])}; }
;             bf16_t* kdst = KET + tile * (256 * 64) + (size_t)dq * 64 + i0;
; #pragma unroll
;             for (int jx = 0; jx < 4; ++jx)
;                 *(u32x4*)(kdst + jx * 64) = (u32x4){pg8::cvt_pk_bf16(kf[jx][0], kf[jx][1]), pg8::cvt_pk_bf16(kf[jx][2], kf[jx][3]), pg8::cvt_pk_bf16(kf[jx][4], kf[jx][5]), pg8::cvt_pk_bf16(kf[jx][6], kf[jx][7])};
;             if (i0 == 0) *(f32x4*)(DEC + tile * 256 + dq) = etot;
	v_lshlrev_b32_e32 v177, 16, v150
	v_cndmask_b32_e64 v160, v179, v160, s[54:55]
	v_lshlrev_b32_e32 v179, 16, v152
	v_mul_f32_e32 v158, v158, v177
	v_mul_f32_e32 v177, v181, v179
	v_rcp_f32_e32 v179, v159
	v_cndmask_b32_e64 v161, v180, v161, s[54:55]
	v_and_b32_e32 v150, 0xffff0000, v150
	v_and_b32_e32 v152, 0xffff0000, v152
	v_mul_f32_e32 v150, v159, v150
	v_mul_f32_e32 v159, 0x3fb8aa3b, v160
	v_mul_f32_e32 v160, v179, v152
	v_mul_f32_e32 v152, 0x3fb8aa3b, v161
	v_exp_f32_e32 v159, v159
	v_exp_f32_e32 v152, v152
	v_lshlrev_b32_e32 v178, 16, v151
	v_and_b32_e32 v151, 0xffff0000, v151
	v_rcp_f32_e32 v161, v159
	v_mul_f32_e32 v159, v159, v178
	v_rcp_f32_e32 v178, v152
	v_mul_f32_e32 v151, v152, v151
	v_mul_f32_e32 v150, 0x3d800000, v150
	v_mul_f32_e32 v151, 0x3d800000, v151
	v_lshlrev_b32_e32 v180, 16, v153
	v_and_b32_e32 v153, 0xffff0000, v153
	v_mul_f32_e32 v158, 0x3d800000, v158
	v_mul_f32_e32 v159, 0x3d800000, v159
	v_cvt_pk_bf16_f32 v150, v158, v150
	v_cvt_pk_bf16_f32 v151, v159, v151
	v_mul_f32_e32 v161, v161, v180
	v_mul_f32_e32 v178, v178, v153
	ds_write_b64 v138, v[150:151] offset:8784
	v_cvt_pk_bf16_f32 v150, v177, v160
	v_cvt_pk_bf16_f32 v151, v161, v178
	ds_write_b64 v138, v[150:151] offset:42576
	ds_read_b128 v[150:153], v144
	v_sub_f32_e32 v181, v15, v154
	v_sub_f32_e32 v182, v14, v155
	v_add_u32_e32 v154, 0x60, v138
	v_sub_f32_e32 v183, v13, v156
	s_waitcnt lgkmcnt(0)
	v_pk_add_f32 v[158:159], v[10:11], v[150:151]
	v_sub_f32_e32 v184, v12, v157
	v_cndmask_b32_e64 v158, v181, v158, s[54:55]
	v_mul_f32_e32 v158, 0x3fb8aa3b, v158
	v_exp_f32_e32 v158, v158
	ds_read2st64_b64 v[154:157], v154 offset0:18 offset1:84
	v_cndmask_b32_e64 v159, v182, v159, s[54:55]
	v_mul_f32_e32 v159, 0x3fb8aa3b, v159
	v_rcp_f32_e32 v185, v158
	v_exp_f32_e32 v159, v159
	v_mul_f32_e32 v179, v1, v160
	v_mul_f32_e32 v180, v2, v161
	v_pk_add_f32 v[160:161], v[8:9], v[152:153]
	s_waitcnt lgkmcnt(0)
	v_lshlrev_b32_e32 v181, 16, v154
	v_cndmask_b32_e64 v160, v183, v160, s[54:55]
	v_lshlrev_b32_e32 v183, 16, v156
	v_mul_f32_e32 v158, v158, v181
	v_mul_f32_e32 v181, v185, v183
	v_rcp_f32_e32 v183, v159
	v_cndmask_b32_e64 v161, v184, v161, s[54:55]
	v_and_b32_e32 v154, 0xffff0000, v154
	v_and_b32_e32 v156, 0xffff0000, v156
	v_mul_f32_e32 v154, v159, v154
	v_mul_f32_e32 v159, 0x3fb8aa3b, v160
	v_mul_f32_e32 v160, v183, v156
	v_mul_f32_e32 v156, 0x3fb8aa3b, v161
	v_exp_f32_e32 v159, v159
	v_exp_f32_e32 v156, v156
	v_lshlrev_b32_e32 v182, 16, v155
	v_and_b32_e32 v155, 0xffff0000, v155
	v_rcp_f32_e32 v161, v159
	v_mul_f32_e32 v159, v159, v182
	v_rcp_f32_e32 v182, v156
	v_mul_f32_e32 v155, v156, v155
	v_mul_f32_e32 v154, 0x3d800000, v154
	v_mul_f32_e32 v155, 0x3d800000, v155
	v_lshlrev_b32_e32 v184, 16, v157
	v_and_b32_e32 v157, 0xffff0000, v157
	v_mul_f32_e32 v158, 0x3d800000, v158
	v_mul_f32_e32 v159, 0x3d800000, v159
	v_cvt_pk_bf16_f32 v154, v158, v154
	v_cvt_pk_bf16_f32 v155, v159, v155
	v_mul_f32_e32 v161, v161, v184
	v_mul_f32_e32 v182, v182, v157
	ds_write_b64 v138, v[154:155] offset:9312
	v_cvt_pk_bf16_f32 v154, v181, v160
	v_cvt_pk_bf16_f32 v155, v161, v182
	ds_write_b64 v138, v[154:155] offset:43104
	ds_read_b128 v[154:157], v145
	v_sub_f32_e32 v15, v15, v150
	v_sub_f32_e32 v14, v14, v151
	v_sub_f32_e32 v13, v13, v152
	v_sub_f32_e32 v12, v12, v153
	s_waitcnt lgkmcnt(0)
	v_pk_add_f32 v[154:155], v[10:11], v[154:155]
	v_pk_add_f32 v[156:157], v[8:9], v[156:157]
	v_cndmask_b32_e64 v15, v15, v154, s[54:55]
	v_mul_f32_e32 v15, 0x3fb8aa3b, v15
	v_exp_f32_e32 v15, v15
	ds_read2st64_b64 v[8:11], v146 offset0:12 offset1:78
	v_cndmask_b32_e64 v14, v14, v155, s[54:55]
	v_mul_f32_e32 v14, 0x3fb8aa3b, v14
	v_rcp_f32_e32 v154, v15
	v_exp_f32_e32 v14, v14
	v_cndmask_b32_e64 v13, v13, v156, s[54:55]
	s_waitcnt lgkmcnt(0)
	v_lshlrev_b32_e32 v150, 16, v8
	v_lshlrev_b32_e32 v152, 16, v10
	v_mul_f32_e32 v13, 0x3fb8aa3b, v13
	v_mul_f32_e32 v15, v15, v150
	v_mul_f32_e32 v150, v154, v152
	v_rcp_f32_e32 v154, v14
	v_exp_f32_e32 v13, v13
	v_cndmask_b32_e64 v12, v12, v157, s[54:55]
	v_and_b32_e32 v10, 0xffff0000, v10
	v_mul_f32_e32 v12, 0x3fb8aa3b, v12
	v_mul_f32_e32 v10, v154, v10
	v_rcp_f32_e32 v154, v13
	v_exp_f32_e32 v12, v12
	v_lshlrev_b32_e32 v151, 16, v9
	v_lshlrev_b32_e32 v153, 16, v11
	v_and_b32_e32 v8, 0xffff0000, v8
	v_and_b32_e32 v9, 0xffff0000, v9
	v_mul_f32_e32 v13, v13, v151
	v_mul_f32_e32 v151, v154, v153
	v_rcp_f32_e32 v153, v12
	v_mul_f32_e32 v8, v14, v8
	v_mul_f32_e32 v9, v12, v9
	v_mul_f32_e32 v8, 0x3d800000, v8
	v_mul_f32_e32 v9, 0x3d800000, v9
	v_and_b32_e32 v11, 0xffff0000, v11
	v_mul_f32_e32 v15, 0x3d800000, v15
	v_mul_f32_e32 v13, 0x3d800000, v13
	v_cvt_pk_bf16_f32 v8, v15, v8
	v_cvt_pk_bf16_f32 v9, v13, v9
	s_lshl_b64 s[0:1], s[94:95], 15
	v_mul_f32_e32 v6, v1, v6
	v_mul_f32_e32 v11, v153, v11
	ds_write_b64 v146, v[8:9] offset:6144
	v_cvt_pk_bf16_f32 v8, v150, v10
	v_cvt_pk_bf16_f32 v9, v151, v11
	v_lshl_add_u64 v[12:13], v[92:93], 0, s[0:1]
	v_mul_f32_e32 v162, v0, v162
	v_mul_f32_e32 v169, v0, v169
	v_mul_f32_e32 v173, v0, v173
	v_mul_f32_e32 v177, v0, v177
	v_mul_f32_e32 v158, v0, v181
	v_mul_f32_e32 v152, v0, v150
	v_mul_f32_e32 v14, v1, v10
	v_mul_f32_e32 v153, v3, v11
	ds_write_b64 v146, v[8:9] offset:39936
	v_cvt_pk_bf16_f32 v8, v7, v163
	v_cvt_pk_bf16_f32 v9, v162, v169
	v_cvt_pk_bf16_f32 v10, v173, v177
	v_cvt_pk_bf16_f32 v11, v158, v152
	global_store_dwordx4 v[12:13], v[8:11], off
	v_cvt_pk_bf16_f32 v6, v6, v164
	v_cvt_pk_bf16_f32 v7, v167, v171
	v_mul_f32_e32 v159, v1, v160
	v_mul_f32_e32 v166, v3, v166
	v_cvt_pk_bf16_f32 v8, v175, v179
	v_cvt_pk_bf16_f32 v9, v159, v14
	global_store_dwordx4 v[12:13], v[6:9], off offset:128
	v_mul_f32_e32 v170, v3, v170
	v_mul_f32_e32 v174, v3, v174
	v_cvt_pk_bf16_f32 v6, v5, v165
	v_cvt_pk_bf16_f32 v7, v168, v172
	v_mul_f32_e32 v178, v3, v178
	v_mul_f32_e32 v160, v2, v161
	v_mul_f32_e32 v161, v3, v182
	v_mul_f32_e32 v154, v2, v151
	v_cvt_pk_bf16_f32 v8, v176, v180
	v_cvt_pk_bf16_f32 v9, v160, v154
	global_store_dwordx4 v[12:13], v[6:9], off offset:256
	v_cvt_pk_bf16_f32 v4, v4, v105
	v_cvt_pk_bf16_f32 v5, v166, v170
	s_nop 1
	v_cvt_pk_bf16_f32 v6, v174, v178
	v_cvt_pk_bf16_f32 v7, v161, v153
	global_store_dwordx4 v[12:13], v[4:7], off offset:384
	s_and_saveexec_b64 s[0:1], s[52:53]
	s_cbranch_execz .LBB0_678
	s_lshl_b64 s[12:13], s[94:95], 10
	v_lshl_add_u64 v[4:5], v[94:95], 0, s[12:13]
	global_store_dwordx4 v[4:5], v[0:3], off

; __device__ __forceinline__ int mk_tid() { int t = (int)threadIdx.x; asm volatile("" : "+v"(t)); return t; }
; #define LAS __attribute__((address_space(3)))
; __device__ __forceinline__ void gla_scan_phase(const Ctx& c, LAS unsigned char* lds) {
;     bf16_t* Pw = (bf16_t*)(c.ws + WS_P); bf16_t* A = (bf16_t*)(c.ws + WS_A);
;     const unsigned char* QD = c.ws + WS_X + X_QD; const unsigned char* KET = c.ws + WS_X + X_KET; const unsigned char* PM = c.ws + WS_X + X_PM; const float* DEC = (const float*)(c.ws + WS_X + X_DEC);
;     const int tid = c.tid, wid = c.wave, lane = c.lane, r32 = lane & 31, hi = lane >> 5;
;     for (int u = blockIdx.x; u < 256; u += c.G) {
;         const int combo = (u & 7) * 4 + ((u >> 3) >> 3), es = (u >> 3) & 7;
;         const int dir = combo >> 4, bh = combo & 15, b = bh >> 2, h = bh & 3;
;         const size_t tb = (size_t)(dir * 16 + bh) * NCH;
;         u32x4 rq[4], rk[4], rp, rv, rd = {0u, 0u, 0u, 0u};
;     ...
;         __syncthreads();
;         for (int i = tid; i < 33792 / 16; i += 512) *(LAS u32x4*)(lds + SC_ST + i * 16) = (u32x4){0u, 0u, 0u, 0u};
;         f32x16 sacc[4] = {};
;         { const int c0 = dir ? NCH - 1 : 0; SC_LOAD(c0, mk_tid()); SC_STORE(mk_tid()); SC_LOAD(dir ? NCH - 2 : 1, mk_tid()); }
;         __syncthreads();
.LBB0_737:
	s_or_b64 exec, exec, s[2:3]
	s_waitcnt lgkmcnt(0)
	s_barrier
	s_nop 0
	s_nop 0
	s_nop 0
	s_nop 0
	s_nop 0
	s_nop 0
	s_nop 0
	s_nop 0
.LBB0_738:
	s_cmp_lt_i32 s74, 12
	s_cselect_b64 s[0:1], -1, 0
	s_cmp_gt_i32 s75, 11
	s_cselect_b64 s[2:3], -1, 0
	s_and_b64 s[0:1], s[0:1], s[2:3]
	s_andn2_b64 vcc, exec, s[0:1]
	v_writelane_b32 v254, s76, 38
	s_cbranch_vccnz .LBB0_854
	v_mov_b32_e32 v1, v200
	s_cmpk_gt_i32 s76, 0xff
	v_readfirstlane_b32 s0, v1
	s_cbranch_scc1 .LBB0_800
	s_add_u32 s16, s72, 0x6300000
	s_addc_u32 s17, s73, 0
	s_add_u32 s1, s72, 0x2200000
	v_writelane_b32 v254, s1, 30
	s_addc_u32 s1, s73, 0
	s_add_u32 s79, s72, 0x12500000
	s_addc_u32 s80, s73, 0
	s_add_u32 s81, s72, 0x16600000
	s_addc_u32 s82, s73, 0
	s_add_u32 s83, s72, 0x1a700000
	s_addc_u32 s90, s73, 0
	s_add_u32 s91, s72, 0x1b800000
	v_writelane_b32 v254, s1, 40
	s_addc_u32 s92, s73, 0
	s_ashr_i32 s0, s0, 6
	s_movk_i32 s1, 0x840
	v_cmp_gt_i32_e64 s[2:3], s1, v1
	s_cmp_lt_i32 s0, 4
	v_bfe_u32 v3, v1, 5, 1
	v_writelane_b32 v254, s2, 42
	s_cselect_b64 s[18:19], -1, 0
	s_cmp_gt_i32 s0, 3
	v_and_b32_e32 v2, 31, v1
	v_writelane_b32 v254, s3, 43
	s_cselect_b64 s[20:21], -1, 0
	s_add_i32 s1, s0, -4
	v_lshlrev_b32_e32 v196, 4, v3
	s_add_i32 s3, 0, 0x1e000
	s_lshl_b32 s2, s1, 8
	v_add_u32_e32 v4, s3, v196
	v_lshl_or_b32 v0, s1, 6, v2
	s_lshl_b32 s1, s0, 5
	s_lshl_b32 s3, s0, 4
	s_lshl_b32 s97, s0, 7
	s_add_i32 s94, 0, 0x13800
	s_and_b32 s1, s1, 32
	v_mov_b32_e32 v8, s3
	s_add_i32 s96, 0, 0x11400
	s_add_i32 s3, 0, 0x15c00
	s_add_i32 s33, s97, 0xfffffe00
	s_add_i32 s76, s97, 0xfffffe40
	s_bitcmp1_b32 s0, 0
	s_movk_i32 s93, 0x90
	s_movk_i32 s4, 0xffe0
	s_cselect_b64 s[24:25], -1, 0
	s_lshr_b32 s0, s0, 1
	v_mul_lo_u32 v0, v0, s93
	v_or_b32_e32 v7, s1, v2
	s_movk_i32 s95, 0x210
	v_bfi_b32 v198, s4, v8, v1
	v_mov_b32_e32 v8, s96
	s_mulk_i32 s0, 0x4200
	v_add_u32_e32 v5, 0, v0
	v_mov_b32_e32 v0, s94
	v_mad_u32_u24 v197, v7, s95, 0
	v_mad_u32_u24 v7, v7, s93, v8
	v_mul_lo_u32 v8, v198, s93
	s_add_i32 s0, s0, 0
	v_mad_u32_u24 v6, v2, s93, v0
	v_mov_b32_e32 v0, 0
	v_add_u32_e32 v8, s94, v8
	v_lshlrev_b32_e32 v9, 3, v3
	v_lshl_or_b32 v199, v3, 2, s1
	v_mul_u32_u24_e32 v3, 0x210, v2
	v_add_u32_e32 v202, 0xfffffe00, v1
	v_lshl_add_u32 v203, v1, 4, s3
	v_mov_b32_e32 v1, s0
	s_mov_b32 s23, 0
	v_add3_u32 v201, s3, v9, v3
	v_cmp_lt_u32_e64 s[4:5], 30, v199
	v_cmp_lt_u32_e64 s[6:7], 29, v199
	v_cmp_lt_u32_e64 s[8:9], 28, v199
	v_cmp_lt_u32_e64 s[10:11], 22, v199
	v_cmp_lt_u32_e64 s[12:13], 21, v199
	v_cmp_lt_u32_e64 s[14:15], 20, v199
	v_mad_u32_u24 v204, v2, s95, v1
	s_waitcnt vmcnt(0)
	v_mov_b32_e32 v144, 0
	v_mov_b32_e32 v145, v0
	v_mov_b32_e32 v146, v0
	v_mov_b32_e32 v147, v0
	s_mov_b64 s[26:27], 0x2000
	s_mov_b64 s[28:29], 0x4000
	s_mov_b64 s[30:31], 0x6000
	s_movk_i32 s77, 0x3040
	v_add_u32_e32 v205, s2, v4
	v_add_u32_e32 v206, v5, v196
	v_add_u32_e32 v207, v6, v196
	v_add_u32_e32 v208, v7, v196
	v_add_u32_e32 v209, v8, v196
	v_readlane_b32 s78, v254, 38
	s_branch .LBB0_742

; #define LAS __attribute__((address_space(3)))
; __device__ __forceinline__ void gla_prep_phase(const Ctx& c, int j, LAS unsigned char* lds) {
;     ...
;         float up[16];
; #pragma unroll
;         for (int r = 0; r < 16; ++r) up[r] = pup[r];
;         const float bias = pbias;
;         { const int un = u + c.G; have = un < 2 * 16 * NCH; if (have) PREP_FETCH(un); }
;         __syncthreads();
;         float run = 0.f;
; #pragma unroll 4
;         for (int ii = 0; ii < 32; ++ii) { const int i = half * 32 + ii; float z = bias;
; #pragma unroll
;             for (int r = 0; r < 16; r += 4) { const f32x4 l4 = *(const LAS f32x4*)(LR + i * 16 + r); z += l4.x * up[r] + l4.y * up[r + 1] + l4.z * up[r + 2] + l4.w * up[r + 3]; }
;             const float ls = fminf(z, 0.f) - __logf(1.f + __expf(-fabsf(z)));
;             const bool valid = (ch > 0) || (i >= 48);
;             run += valid ? ls * (1.f / 16.f) : 0.f; CUM[i * 256 + d] = run; }
.LBB0_1628:
	s_cmp_gt_i32 s95, 0
	s_mov_b32 s0, 0
	v_mov_b32_e32 v152, 0
	s_cselect_b64 s[66:67], -1, 0
	v_mov_b32_e32 v150, v135
	v_mov_b32_e32 v151, v134
	v_mov_b32_e32 v202, v2
	v_mov_b32_e32 v203, v0
	v_mov_b32_e32 v204, v4
	v_mov_b32_e32 v205, v6
	v_mov_b32_e32 v206, v3
	v_mov_b32_e32 v207, v1
	v_mov_b32_e32 v208, v5
	v_mov_b32_e32 v209, v7
	v_mov_b32_e32 v210, v10
	v_mov_b32_e32 v211, v8
	v_mov_b32_e32 v212, v12
	v_mov_b32_e32 v213, v14
	v_mov_b32_e32 v214, v11
	v_mov_b32_e32 v215, v9
	v_mov_b32_e32 v216, v13
	v_mov_b32_e32 v217, v15
	s_waitcnt lgkmcnt(0)
	s_barrier
	s_cmp_lg_u64 s[66:67], 0
	s_cbranch_scc1 .Lprep_fast_b
.LBB0_1629:
	v_add_u32_e32 v173, 0, v150
	ds_read_b128 v[154:157], v173
	ds_read_b128 v[158:161], v173 offset:16
	ds_read_b128 v[162:165], v173 offset:32
	ds_read_b128 v[166:169], v173 offset:48
	v_add_u32_e32 v172, s0, v53
	v_add_u32_e32 v171, 0, v151
	v_add_u32_e32 v174, 2, v172
	s_add_i32 s0, s0, 4
	s_waitcnt lgkmcnt(0)
	v_pk_mul_f32 v[218:219], v[202:203], v[154:155]
	v_pk_mul_f32 v[220:221], v[210:211], v[162:163]
	v_pk_fma_f32 v[218:219], v[204:205], v[156:157], v[218:219]
	v_pk_fma_f32 v[220:221], v[212:213], v[164:165], v[220:221]
	v_pk_fma_f32 v[218:219], v[206:207], v[158:159], v[218:219]
	v_pk_fma_f32 v[220:221], v[214:215], v[166:167], v[220:221]
	v_pk_fma_f32 v[218:219], v[208:209], v[160:161], v[218:219]
	v_pk_fma_f32 v[220:221], v[216:217], v[168:169], v[220:221]
	s_nop 0
	v_pk_add_f32 v[218:219], v[218:219], v[220:221]
	s_nop 0
	v_add_f32_e32 v153, v105, v218
	v_add_f32_e32 v153, v153, v219
	v_min_f32_e32 v154, 0, v153
	v_mul_f32_e64 v153, |v153|, s88
	v_exp_f32_e32 v153, v153
	v_add_u32_e32 v151, 0x1000, v151
	v_add_u32_e32 v150, 0x100, v150
	v_add_f32_e32 v153, 1.0, v153
	v_log_f32_e32 v153, v153
	s_nop 0
	v_mul_f32_e32 v155, 0x3f317217, v153
	v_fma_f32 v155, v153, s90, -v155
	v_fmac_f32_e32 v155, 0x3377d1cf, v153
	v_fmac_f32_e32 v155, 0x3f317217, v153
	v_sub_f32_e32 v153, v154, v155
	v_cmp_lt_i32_e32 vcc, 47, v172
	s_or_b64 vcc, s[66:67], vcc
	v_mul_f32_e32 v153, 0x3d800000, v153
	v_cndmask_b32_e32 v153, 0, v153, vcc
	v_add_f32_e32 v170, v152, v153
	v_add_u32_e32 v152, 0x12000, v171
	ds_write_b32 v152, v170
	ds_read_b128 v[152:155], v173 offset:64
	ds_read_b128 v[156:159], v173 offset:80
	ds_read_b128 v[160:163], v173 offset:96
	ds_read_b128 v[164:167], v173 offset:112
	s_waitcnt lgkmcnt(0)
	v_pk_mul_f32 v[218:219], v[202:203], v[152:153]
	v_pk_mul_f32 v[220:221], v[210:211], v[160:161]
	v_pk_fma_f32 v[218:219], v[204:205], v[154:155], v[218:219]
	v_pk_fma_f32 v[220:221], v[212:213], v[162:163], v[220:221]
	v_pk_fma_f32 v[218:219], v[206:207], v[156:157], v[218:219]
	v_pk_fma_f32 v[220:221], v[214:215], v[164:165], v[220:221]
	v_pk_fma_f32 v[218:219], v[208:209], v[158:159], v[218:219]
	v_pk_fma_f32 v[220:221], v[216:217], v[166:167], v[220:221]
	s_nop 0
	v_pk_add_f32 v[218:219], v[218:219], v[220:221]
	s_nop 0
	v_add_f32_e32 v152, v105, v218
	v_add_f32_e32 v152, v152, v219
	v_min_f32_e32 v153, 0, v152
	v_mul_f32_e64 v152, |v152|, s88
	v_exp_f32_e32 v152, v152
	s_nop 0
	v_add_f32_e32 v152, 1.0, v152
	v_log_f32_e32 v152, v152
	s_nop 0
	v_mul_f32_e32 v154, 0x3f317217, v152
	v_fma_f32 v154, v152, s90, -v154
	v_fmac_f32_e32 v154, 0x3377d1cf, v152
	v_fmac_f32_e32 v154, 0x3f317217, v152
	v_sub_f32_e32 v152, v153, v154
	v_cmp_lt_i32_e32 vcc, 46, v172
	s_or_b64 vcc, s[66:67], vcc
	v_mul_f32_e32 v152, 0x3d800000, v152
	v_cndmask_b32_e32 v152, 0, v152, vcc
	v_add_f32_e32 v170, v170, v152
	v_add_u32_e32 v152, 0x12400, v171
	ds_write_b32 v152, v170
	ds_read_b128 v[152:155], v173 offset:128
	ds_read_b128 v[156:159], v173 offset:144
	ds_read_b128 v[160:163], v173 offset:160
	ds_read_b128 v[164:167], v173 offset:176
	v_add_u32_e32 v172, 3, v172
	s_waitcnt lgkmcnt(0)
	v_pk_mul_f32 v[218:219], v[202:203], v[152:153]
	v_pk_mul_f32 v[220:221], v[210:211], v[160:161]
	v_pk_fma_f32 v[218:219], v[204:205], v[154:155], v[218:219]
	v_pk_fma_f32 v[220:221], v[212:213], v[162:163], v[220:221]
	v_pk_fma_f32 v[218:219], v[206:207], v[156:157], v[218:219]
	v_pk_fma_f32 v[220:221], v[214:215], v[164:165], v[220:221]
	v_pk_fma_f32 v[218:219], v[208:209], v[158:159], v[218:219]
	v_pk_fma_f32 v[220:221], v[216:217], v[166:167], v[220:221]
	s_nop 0
	v_pk_add_f32 v[218:219], v[218:219], v[220:221]
	s_nop 0
	v_add_f32_e32 v152, v105, v218
	v_add_f32_e32 v152, v152, v219
	v_min_f32_e32 v153, 0, v152
	v_mul_f32_e64 v152, |v152|, s88
	v_exp_f32_e32 v152, v152
	s_nop 0
	v_add_f32_e32 v152, 1.0, v152
	v_log_f32_e32 v152, v152
	s_nop 0
	v_mul_f32_e32 v154, 0x3f317217, v152
	v_fma_f32 v154, v152, s90, -v154
	v_fmac_f32_e32 v154, 0x3377d1cf, v152
	v_fmac_f32_e32 v154, 0x3f317217, v152
	v_sub_f32_e32 v152, v153, v154
	v_cmp_lt_i32_e32 vcc, 47, v174
	s_or_b64 vcc, s[66:67], vcc
	v_mul_f32_e32 v152, 0x3d800000, v152
	v_cndmask_b32_e32 v152, 0, v152, vcc
	v_add_f32_e32 v170, v170, v152
	v_add_u32_e32 v152, 0x12800, v171
	ds_write_b32 v152, v170
	ds_read_b128 v[152:155], v173 offset:192
	ds_read_b128 v[156:159], v173 offset:208
	ds_read_b128 v[160:163], v173 offset:224
	ds_read_b128 v[164:167], v173 offset:240
	s_waitcnt lgkmcnt(0)
	v_pk_mul_f32 v[218:219], v[202:203], v[152:153]
	v_pk_mul_f32 v[220:221], v[210:211], v[160:161]
	v_pk_fma_f32 v[218:219], v[204:205], v[154:155], v[218:219]
	v_pk_fma_f32 v[220:221], v[212:213], v[162:163], v[220:221]
	v_pk_fma_f32 v[218:219], v[206:207], v[156:157], v[218:219]
	v_pk_fma_f32 v[220:221], v[214:215], v[164:165], v[220:221]
	v_pk_fma_f32 v[218:219], v[208:209], v[158:159], v[218:219]
	v_pk_fma_f32 v[220:221], v[216:217], v[166:167], v[220:221]
	s_nop 0
	v_pk_add_f32 v[218:219], v[218:219], v[220:221]
	s_nop 0
	v_add_f32_e32 v152, v105, v218
	v_add_f32_e32 v152, v152, v219
	v_min_f32_e32 v153, 0, v152
	v_mul_f32_e64 v152, |v152|, s88
	v_exp_f32_e32 v152, v152
	s_nop 0
	v_add_f32_e32 v152, 1.0, v152
	v_log_f32_e32 v152, v152
	s_nop 0
	v_mul_f32_e32 v154, 0x3f317217, v152
	v_fma_f32 v154, v152, s90, -v154
	v_fmac_f32_e32 v154, 0x3377d1cf, v152
	v_fmac_f32_e32 v154, 0x3f317217, v152
	v_sub_f32_e32 v152, v153, v154
	v_cmp_lt_i32_e32 vcc, 47, v172
	s_or_b64 vcc, s[66:67], vcc
	v_mul_f32_e32 v152, 0x3d800000, v152
	v_cndmask_b32_e32 v152, 0, v152, vcc
	v_add_f32_e32 v152, v170, v152
	v_add_u32_e32 v153, 0x12c00, v171
	s_cmp_eq_u32 s0, 32
	ds_write_b32 v153, v152
	s_cbranch_scc0 .LBB0_1629
	s_branch .Lprep_join_b
; #define LAS __attribute__((address_space(3)))
; __device__ __forceinline__ void gla_prep_phase(const Ctx& c, int j, LAS unsigned char* lds) {
;     ...
;         for (int ii = 0; ii < 32; ++ii) { const int i = half * 32 + ii; float z = bias;
; #pragma unroll
;             for (int r = 0; r < 16; r += 4) { const f32x4 l4 = *(const LAS f32x4*)(LR + i * 16 + r); z += l4.x * up[r] + l4.y * up[r + 1] + l4.z * up[r + 2] + l4.w * up[r + 3]; }
;             const float ls = fminf(z, 0.f) - __logf(1.f + __expf(-fabsf(z)));
;             const bool valid = (ch > 0) || (i >= 48);
;             run += valid ? ls * (1.f / 16.f) : 0.f; CUM[i * 256 + d] = run; }
.Lprep_fast_b:
	v_add_u32_e32 v173, 0, v150
	ds_read_b128 v[154:157], v173
	ds_read_b128 v[158:161], v173 offset:16
	ds_read_b128 v[162:165], v173 offset:32
	ds_read_b128 v[166:169], v173 offset:48
	v_add_u32_e32 v171, 0, v151
	s_add_i32 s0, s0, 4
	s_waitcnt lgkmcnt(0)
	v_pk_mul_f32 v[218:219], v[202:203], v[154:155]
	v_pk_mul_f32 v[220:221], v[210:211], v[162:163]
	v_pk_fma_f32 v[218:219], v[204:205], v[156:157], v[218:219]
	v_pk_fma_f32 v[220:221], v[212:213], v[164:165], v[220:221]
	v_pk_fma_f32 v[218:219], v[206:207], v[158:159], v[218:219]
	v_pk_fma_f32 v[220:221], v[214:215], v[166:167], v[220:221]
	v_pk_fma_f32 v[218:219], v[208:209], v[160:161], v[218:219]
	v_pk_fma_f32 v[220:221], v[216:217], v[168:169], v[220:221]
	s_nop 0
	v_pk_add_f32 v[218:219], v[218:219], v[220:221]
	s_nop 0
	v_add_f32_e32 v153, v105, v218
	v_add_f32_e32 v153, v153, v219
	v_min_f32_e32 v154, 0, v153
	v_mul_f32_e64 v153, |v153|, s88
	v_exp_f32_e32 v153, v153
	v_add_u32_e32 v151, 0x1000, v151
	v_add_u32_e32 v150, 0x100, v150
	v_add_f32_e32 v153, 1.0, v153
	v_log_f32_e32 v153, v153
	s_nop 0
	v_mul_f32_e32 v155, 0x3f317217, v153
	v_fma_f32 v155, v153, s90, -v155
	v_fmac_f32_e32 v155, 0x3377d1cf, v153
	v_fmac_f32_e32 v155, 0x3f317217, v153
	v_sub_f32_e32 v153, v154, v155
	v_mul_f32_e32 v153, 0x3d800000, v153
	v_add_f32_e32 v170, v152, v153
	v_add_u32_e32 v152, 0x12000, v171
	ds_write_b32 v152, v170
	ds_read_b128 v[152:155], v173 offset:64
	ds_read_b128 v[156:159], v173 offset:80
	ds_read_b128 v[160:163], v173 offset:96
	ds_read_b128 v[164:167], v173 offset:112
	s_waitcnt lgkmcnt(0)
	v_pk_mul_f32 v[218:219], v[202:203], v[152:153]
	v_pk_mul_f32 v[220:221], v[210:211], v[160:161]
	v_pk_fma_f32 v[218:219], v[204:205], v[154:155], v[218:219]
	v_pk_fma_f32 v[220:221], v[212:213], v[162:163], v[220:221]
	v_pk_fma_f32 v[218:219], v[206:207], v[156:157], v[218:219]
	v_pk_fma_f32 v[220:221], v[214:215], v[164:165], v[220:221]
	v_pk_fma_f32 v[218:219], v[208:209], v[158:159], v[218:219]
	v_pk_fma_f32 v[220:221], v[216:217], v[166:167], v[220:221]
	s_nop 0
	v_pk_add_f32 v[218:219], v[218:219], v[220:221]
	s_nop 0
	v_add_f32_e32 v152, v105, v218
	v_add_f32_e32 v152, v152, v219
	v_min_f32_e32 v153, 0, v152
	v_mul_f32_e64 v152, |v152|, s88
	v_exp_f32_e32 v152, v152
	s_nop 0
	v_add_f32_e32 v152, 1.0, v152
	v_log_f32_e32 v152, v152
	s_nop 0
	v_mul_f32_e32 v154, 0x3f317217, v152
	v_fma_f32 v154, v152, s90, -v154
	v_fmac_f32_e32 v154, 0x3377d1cf, v152
	v_fmac_f32_e32 v154, 0x3f317217, v152
	v_sub_f32_e32 v152, v153, v154
	v_mul_f32_e32 v152, 0x3d800000, v152
	v_add_f32_e32 v170, v170, v152
	v_add_u32_e32 v152, 0x12400, v171
	ds_write_b32 v152, v170
	ds_read_b128 v[152:155], v173 offset:128
	ds_read_b128 v[156:159], v173 offset:144
	ds_read_b128 v[160:163], v173 offset:160
	ds_read_b128 v[164:167], v173 offset:176
	s_waitcnt lgkmcnt(0)
	v_pk_mul_f32 v[218:219], v[202:203], v[152:153]
	v_pk_mul_f32 v[220:221], v[210:211], v[160:161]
	v_pk_fma_f32 v[218:219], v[204:205], v[154:155], v[218:219]
	v_pk_fma_f32 v[220:221], v[212:213], v[162:163], v[220:221]
	v_pk_fma_f32 v[218:219], v[206:207], v[156:157], v[218:219]
	v_pk_fma_f32 v[220:221], v[214:215], v[164:165], v[220:221]
	v_pk_fma_f32 v[218:219], v[208:209], v[158:159], v[218:219]
	v_pk_fma_f32 v[220:221], v[216:217], v[166:167], v[220:221]
	s_nop 0
	v_pk_add_f32 v[218:219], v[218:219], v[220:221]
	s_nop 0
	v_add_f32_e32 v152, v105, v218
	v_add_f32_e32 v152, v152, v219
	v_min_f32_e32 v153, 0, v152
	v_mul_f32_e64 v152, |v152|, s88
	v_exp_f32_e32 v152, v152
	s_nop 0
	v_add_f32_e32 v152, 1.0, v152
	v_log_f32_e32 v152, v152
	s_nop 0
	v_mul_f32_e32 v154, 0x3f317217, v152
	v_fma_f32 v154, v152, s90, -v154
	v_fmac_f32_e32 v154, 0x3377d1cf, v152
	v_fmac_f32_e32 v154, 0x3f317217, v152
	v_sub_f32_e32 v152, v153, v154
	v_mul_f32_e32 v152, 0x3d800000, v152
	v_add_f32_e32 v170, v170, v152
	v_add_u32_e32 v152, 0x12800, v171
	ds_write_b32 v152, v170
	ds_read_b128 v[152:155], v173 offset:192
	ds_read_b128 v[156:159], v173 offset:208
	ds_read_b128 v[160:163], v173 offset:224
	ds_read_b128 v[164:167], v173 offset:240
	s_waitcnt lgkmcnt(0)
	v_pk_mul_f32 v[218:219], v[202:203], v[152:153]
	v_pk_mul_f32 v[220:221], v[210:211], v[160:161]
	v_pk_fma_f32 v[218:219], v[204:205], v[154:155], v[218:219]
	v_pk_fma_f32 v[220:221], v[212:213], v[162:163], v[220:221]
	v_pk_fma_f32 v[218:219], v[206:207], v[156:157], v[218:219]
	v_pk_fma_f32 v[220:221], v[214:215], v[164:165], v[220:221]
	v_pk_fma_f32 v[218:219], v[208:209], v[158:159], v[218:219]
	v_pk_fma_f32 v[220:221], v[216:217], v[166:167], v[220:221]
	s_nop 0
	v_pk_add_f32 v[218:219], v[218:219], v[220:221]
	s_nop 0
	v_add_f32_e32 v152, v105, v218
	v_add_f32_e32 v152, v152, v219
	v_min_f32_e32 v153, 0, v152
	v_mul_f32_e64 v152, |v152|, s88
	v_exp_f32_e32 v152, v152
	s_nop 0
	v_add_f32_e32 v152, 1.0, v152
	v_log_f32_e32 v152, v152
	s_nop 0
	v_mul_f32_e32 v154, 0x3f317217, v152
	v_fma_f32 v154, v152, s90, -v154
	v_fmac_f32_e32 v154, 0x3377d1cf, v152
	v_fmac_f32_e32 v154, 0x3f317217, v152
	v_sub_f32_e32 v152, v153, v154
	v_mul_f32_e32 v152, 0x3d800000, v152
	v_add_f32_e32 v152, v170, v152
	v_add_u32_e32 v153, 0x12c00, v171
	s_cmp_eq_u32 s0, 32
	ds_write_b32 v153, v152
	s_cbranch_scc0 .Lprep_fast_b
; __device__ __forceinline__ unsigned cvt_pk_bf16(float lo, float hi) { unsigned r; asm volatile("v_cvt_pk_bf16_f32 %0, %1, %2" : "=v"(r) : "v"(lo), "v"(hi)); return r; }
; #define LAS __attribute__((address_space(3)))
; __device__ __forceinline__ void gla_prep_phase(const Ctx& c, int j, LAS unsigned char* lds) {
;     ...
;         TOT[half * 256 + d] = run;
;         __syncthreads();
;         const size_t tile = (size_t)(dir * 16 + bh) * NCH + ch;
;         bf16_t* qdst = QD + tile * (64 * 256);
;         {
;             const int dq = (c.tid & 63) * 4, i0 = (c.tid >> 6) * 8, hf = i0 >> 5;
;             const f32x4 t0 = *(const LAS f32x4*)(TOT + dq), t1 = *(const LAS f32x4*)(TOT + 256 + dq), total = t0 + t1;
;             const f32x4 off0 = hf ? t0 : (f32x4){0.f, 0.f, 0.f, 0.f}, sbase = hf ? t1 : total;
;             f32x4 etot; etot.x = __expf(total.x); etot.y = __expf(total.y); etot.z = __expf(total.z); etot.w = __expf(total.w);
;             f32x4 prev = (i0 & 31) ? *(const LAS f32x4*)(CUM + (i0 - 1) * 256 + dq) : (f32x4){0.f, 0.f, 0.f, 0.f};
;             float kf[4][8];
; #pragma unroll
;             for (int e = 0; e < 8; ++e) { const int i = i0 + e;
;                 const f32x4 incl = *(const LAS f32x4*)(CUM + i * 256 + dq);
;                 const f32x4 cum = (dir == 0) ? (off0 + incl) : (sbase - prev); prev = incl;
;                 const u32x2 qw = *(const LAS u32x2*)(QL + i * 528 + dq * 2), kw = *(const LAS u32x2*)(KL + i * 528 + dq * 2);
;                 const float qv[4] = {__uint_as_float(qw.x << 16), __uint_as_float(qw.x & 0xffff0000u), __uint_as_float(qw.y << 16), __uint_as_float(qw.y & 0xffff0000u)};
;                 const float kv[4] = {__uint_as_float(kw.x << 16), __uint_as_float(kw.x & 0xffff0000u), __uint_as_float(kw.y << 16), __uint_as_float(kw.y & 0xffff0000u)};
;                 float qd[4], ki[4];
; #pragma unroll
;                 for (int jx = 0; jx < 4; ++jx) { const float ec = __expf(cum[jx]), rc = __builtin_amdgcn_rcpf(ec);
;                     qd[jx] = qv[jx] * ec * (1.f / 16.f); ki[jx] = kv[jx] * rc; kf[jx][e] = ki[jx] * etot[jx]; }
;                 *(LAS u32x2*)(QL + i * 528 + dq * 2) = (u32x2){pg8::cvt_pk_bf16(qd[0], qd[1]), pg8::cvt_pk_bf16(qd[2], qd[3])};
;                 *(LAS u32x2*)(KL + i * 528 + dq * 2) = (u32x2){pg8::cvt_pk_bf16(ki[0], ki[1]), pg8::cvt_pk_bf16(ki[2], ki[3])}; }
.Lprep_join_b:
	ds_write_b32 v91, v152 offset:4096
	s_waitcnt lgkmcnt(0)
	s_barrier
	ds_read_b128 v[0:3], v128 offset:4096
	ds_read_b128 v[8:11], v128 offset:5120
	v_mov_b32_e32 v4, 0
	v_mov_b32_e32 v5, 0
	v_mov_b32_e32 v6, 0
	v_mov_b32_e32 v7, 0
	s_and_saveexec_b64 s[0:1], s[38:39]
	ds_read_b128 v[4:7], v132
	s_or_b64 exec, exec, s[0:1]
	s_waitcnt lgkmcnt(0)
	v_pk_add_f32 v[150:151], v[0:1], v[8:9]
	s_lshl_b32 s0, s94, 4
	v_pk_add_f32 v[154:155], v[2:3], v[10:11]
	v_cndmask_b32_e64 v14, v9, v151, s[36:37]
	v_cndmask_b32_e64 v9, v3, 0, s[36:37]
	v_add_u32_e32 v3, v130, v129
	s_add_i32 s0, s0, s96
	v_cndmask_b32_e64 v12, v11, v155, s[36:37]
	v_cndmask_b32_e64 v13, v10, v154, s[36:37]
	v_cndmask_b32_e64 v15, v8, v150, s[36:37]
	v_cndmask_b32_e64 v11, v1, 0, s[36:37]
	v_cndmask_b32_e64 v10, v0, 0, s[36:37]
	v_mul_f32_e32 v0, 0x3fb8aa3b, v150
	v_mul_f32_e32 v1, 0x3fb8aa3b, v151
	ds_read_b128 v[150:153], v3
	s_mul_hi_i32 s1, s0, 0x41
	s_mulk_i32 s0, 0x41
	s_ashr_i32 s33, s95, 31
	s_add_u32 s66, s0, s95
	s_addc_u32 s67, s1, s33
	s_add_i32 s0, s93, 0x40f
	s_cmpk_lt_u32 s0, 0x81f
	v_cndmask_b32_e64 v8, v2, 0, s[36:37]
	v_mul_f32_e32 v2, 0x3fb8aa3b, v154
	v_mul_f32_e32 v3, 0x3fb8aa3b, v155
	s_waitcnt lgkmcnt(0)
	v_pk_add_f32 v[154:155], v[10:11], v[150:151]
	v_sub_f32_e32 v159, v15, v4
	v_sub_f32_e32 v160, v14, v5
	s_cselect_b64 s[54:55], -1, 0
	v_sub_f32_e32 v105, v13, v6
	v_sub_f32_e32 v158, v12, v7
	ds_read2st64_b64 v[4:7], v138 offset0:12 offset1:78
	v_cndmask_b32_e64 v155, v160, v155, s[54:55]
	v_cndmask_b32_e64 v154, v159, v154, s[54:55]
	v_mul_f32_e32 v154, 0x3fb8aa3b, v154
	v_mul_f32_e32 v155, 0x3fb8aa3b, v155
	v_exp_f32_e32 v154, v154
	v_exp_f32_e32 v155, v155
	v_pk_add_f32 v[156:157], v[8:9], v[152:153]
	s_waitcnt lgkmcnt(0)
	v_lshlrev_b32_e32 v159, 16, v6
	v_cndmask_b32_e64 v157, v158, v157, s[54:55]
	v_cndmask_b32_e64 v105, v105, v156, s[54:55]
	v_lshlrev_b32_e32 v156, 16, v4
	v_and_b32_e32 v4, 0xffff0000, v4
	v_rcp_f32_e32 v161, v154
	v_mul_f32_e32 v154, v154, v156
	v_rcp_f32_e32 v156, v155
	v_mul_f32_e32 v4, v155, v4
	v_mul_f32_e32 v105, 0x3fb8aa3b, v105
	v_mul_f32_e32 v155, 0x3fb8aa3b, v157
	v_exp_f32_e32 v105, v105
	v_exp_f32_e32 v155, v155
	v_and_b32_e32 v6, 0xffff0000, v6
	v_lshlrev_b32_e32 v158, 16, v5
	v_and_b32_e32 v5, 0xffff0000, v5
	v_mul_f32_e32 v6, v156, v6
	v_rcp_f32_e32 v156, v105
	v_rcp_f32_e32 v157, v155
	v_mul_f32_e32 v5, v155, v5
	v_mul_f32_e32 v4, 0x3d800000, v4
	v_mul_f32_e32 v105, v105, v158
	v_mul_f32_e32 v5, 0x3d800000, v5
	v_lshlrev_b32_e32 v160, 16, v7
	v_and_b32_e32 v7, 0xffff0000, v7
	v_mul_f32_e32 v154, 0x3d800000, v154
	v_mul_f32_e32 v105, 0x3d800000, v105
	v_cvt_pk_bf16_f32 v4, v154, v4
	v_cvt_pk_bf16_f32 v5, v105, v5
	v_mul_f32_e32 v159, v161, v159
	v_mul_f32_e32 v158, v156, v160
	v_mul_f32_e32 v160, v157, v7
	ds_write_b64 v138, v[4:5] offset:6144
	v_cvt_pk_bf16_f32 v4, v159, v6
	v_cvt_pk_bf16_f32 v5, v158, v160
	ds_write_b64 v138, v[4:5] offset:39936
	ds_read_b128 v[154:157], v139
	v_exp_f32_e32 v0, v0
	v_exp_f32_e32 v2, v2
	v_sub_f32_e32 v105, v15, v150
	v_sub_f32_e32 v162, v14, v151
	v_mul_f32_e32 v7, v0, v159
	v_mul_f32_e32 v5, v2, v158
	s_waitcnt lgkmcnt(0)
	v_pk_add_f32 v[158:159], v[10:11], v[154:155]
	v_add_u32_e32 v150, 16, v138
	v_cndmask_b32_e64 v105, v105, v158, s[54:55]
	v_mul_f32_e32 v105, 0x3fb8aa3b, v105
	v_exp_f32_e32 v105, v105
	v_exp_f32_e32 v3, v3
	v_sub_f32_e32 v163, v13, v152
	v_sub_f32_e32 v164, v12, v153
	ds_read2st64_b64 v[150:153], v150 offset0:13 offset1:79
	v_cndmask_b32_e64 v159, v162, v159, s[54:55]
	v_mul_f32_e32 v159, 0x3fb8aa3b, v159
	v_rcp_f32_e32 v165, v105
	v_exp_f32_e32 v159, v159
	v_mul_f32_e32 v4, v3, v160
	v_pk_add_f32 v[160:161], v[8:9], v[156:157]
	s_waitcnt lgkmcnt(0)
	v_lshlrev_b32_e32 v158, 16, v150
	v_cndmask_b32_e64 v160, v163, v160, s[54:55]
	v_lshlrev_b32_e32 v163, 16, v152
	v_mul_f32_e32 v105, v105, v158
	v_mul_f32_e32 v158, v165, v163
	v_rcp_f32_e32 v163, v159
	v_cndmask_b32_e64 v161, v164, v161, s[54:55]
	v_and_b32_e32 v150, 0xffff0000, v150
	v_and_b32_e32 v152, 0xffff0000, v152
	v_mul_f32_e32 v150, v159, v150
	v_mul_f32_e32 v159, 0x3fb8aa3b, v160
	v_mul_f32_e32 v160, v163, v152
	v_mul_f32_e32 v152, 0x3fb8aa3b, v161
	v_exp_f32_e32 v159, v159
	v_exp_f32_e32 v152, v152
	v_lshlrev_b32_e32 v162, 16, v151
	v_and_b32_e32 v151, 0xffff0000, v151
	v_rcp_f32_e32 v161, v159
	v_mul_f32_e32 v159, v159, v162
	v_rcp_f32_e32 v162, v152
	v_mul_f32_e32 v151, v152, v151
	v_mul_f32_e32 v150, 0x3d800000, v150
	v_mul_f32_e32 v151, 0x3d800000, v151
	v_lshlrev_b32_e32 v164, 16, v153
	v_and_b32_e32 v153, 0xffff0000, v153
	v_mul_f32_e32 v105, 0x3d800000, v105
	v_mul_f32_e32 v159, 0x3d800000, v159
	v_cvt_pk_bf16_f32 v150, v105, v150
	v_cvt_pk_bf16_f32 v151, v159, v151
	v_mul_f32_e32 v161, v161, v164
	v_mul_f32_e32 v162, v162, v153
	ds_write_b64 v138, v[150:151] offset:6672
	v_cvt_pk_bf16_f32 v150, v158, v160
	v_cvt_pk_bf16_f32 v151, v161, v162
	ds_write_b64 v138, v[150:151] offset:40464
	ds_read_b128 v[150:153], v140
	v_mul_f32_e32 v163, v0, v158
	v_mul_f32_e32 v105, v3, v162
	v_sub_f32_e32 v162, v15, v154
	v_sub_f32_e32 v166, v14, v155
	s_waitcnt lgkmcnt(0)
	v_pk_add_f32 v[158:159], v[10:11], v[150:151]
	v_add_u32_e32 v154, 32, v138
	v_cndmask_b32_e64 v158, v162, v158, s[54:55]
	v_mul_f32_e32 v158, 0x3fb8aa3b, v158
	v_exp_f32_e32 v158, v158
	v_exp_f32_e32 v1, v1
	v_sub_f32_e32 v167, v13, v156
	v_sub_f32_e32 v168, v12, v157
	ds_read2st64_b64 v[154:157], v154 offset0:14 offset1:80
	v_cndmask_b32_e64 v159, v166, v159, s[54:55]
	v_mul_f32_e32 v159, 0x3fb8aa3b, v159
	v_rcp_f32_e32 v169, v158
	v_exp_f32_e32 v159, v159
	v_mul_f32_e32 v164, v1, v160
	v_mul_f32_e32 v165, v2, v161
	v_pk_add_f32 v[160:161], v[8:9], v[152:153]
	s_waitcnt lgkmcnt(0)
; __device__ __forceinline__ unsigned cvt_pk_bf16(float lo, float hi) { unsigned r; asm volatile("v_cvt_pk_bf16_f32 %0, %1, %2" : "=v"(r) : "v"(lo), "v"(hi)); return r; }
; #define LAS __attribute__((address_space(3)))
; __device__ __forceinline__ void gla_prep_phase(const Ctx& c, int j, LAS unsigned char* lds) {
;     ...
;             for (int e = 0; e < 8; ++e) { const int i = i0 + e;
;                 const f32x4 incl = *(const LAS f32x4*)(CUM + i * 256 + dq);
;                 const f32x4 cum = (dir == 0) ? (off0 + incl) : (sbase - prev); prev = incl;
;                 const u32x2 qw = *(const LAS u32x2*)(QL + i * 528 + dq * 2), kw = *(const LAS u32x2*)(KL + i * 528 + dq * 2);
;                 const float qv[4] = {__uint_as_float(qw.x << 16), __uint_as_float(qw.x & 0xffff0000u), __uint_as_float(qw.y << 16), __uint_as_float(qw.y & 0xffff0000u)};
;                 const float kv[4] = {__uint_as_float(kw.x << 16), __uint_as_float(kw.x & 0xffff0000u), __uint_as_float(kw.y << 16), __uint_as_float(kw.y & 0xffff0000u)};
;                 float qd[4], ki[4];
; #pragma unroll
;                 for (int jx = 0; jx < 4; ++jx) { const float ec = __expf(cum[jx]), rc = __builtin_amdgcn_rcpf(ec);
;                     qd[jx] = qv[jx] * ec * (1.f / 16.f); ki[jx] = kv[jx] * rc; kf[jx][e] = ki[jx] * etot[jx]; }
;                 *(LAS u32x2*)(QL + i * 528 + dq * 2) = (u32x2){pg8::cvt_pk_bf16(qd[0], qd[1]), pg8::cvt_pk_bf16(qd[2], qd[3])};
;                 *(LAS u32x2*)(KL + i * 528 + dq * 2) = (u32x2){pg8::cvt_pk_bf16(ki[0], ki[1]), pg8::cvt_pk_bf16(ki[2], ki[3])}; }
	v_lshlrev_b32_e32 v162, 16, v154
	v_cndmask_b32_e64 v160, v167, v160, s[54:55]
	v_lshlrev_b32_e32 v167, 16, v156
	v_mul_f32_e32 v158, v158, v162
	v_mul_f32_e32 v162, v169, v167
	v_rcp_f32_e32 v167, v159
	v_cndmask_b32_e64 v161, v168, v161, s[54:55]
	v_and_b32_e32 v154, 0xffff0000, v154
	v_and_b32_e32 v156, 0xffff0000, v156
	v_mul_f32_e32 v154, v159, v154
	v_mul_f32_e32 v159, 0x3fb8aa3b, v160
	v_mul_f32_e32 v160, v167, v156
	v_mul_f32_e32 v156, 0x3fb8aa3b, v161
	v_exp_f32_e32 v159, v159
	v_exp_f32_e32 v156, v156
	v_lshlrev_b32_e32 v166, 16, v155
	v_and_b32_e32 v155, 0xffff0000, v155
	v_rcp_f32_e32 v161, v159
	v_mul_f32_e32 v159, v159, v166
	v_rcp_f32_e32 v166, v156
	v_mul_f32_e32 v155, v156, v155
	v_mul_f32_e32 v154, 0x3d800000, v154
	v_mul_f32_e32 v155, 0x3d800000, v155
	v_lshlrev_b32_e32 v168, 16, v157
	v_and_b32_e32 v157, 0xffff0000, v157
	v_mul_f32_e32 v158, 0x3d800000, v158
	v_mul_f32_e32 v159, 0x3d800000, v159
	v_cvt_pk_bf16_f32 v154, v158, v154
	v_cvt_pk_bf16_f32 v155, v159, v155
	v_mul_f32_e32 v161, v161, v168
	v_mul_f32_e32 v166, v166, v157
	ds_write_b64 v138, v[154:155] offset:7200
	v_cvt_pk_bf16_f32 v154, v162, v160
	v_cvt_pk_bf16_f32 v155, v161, v166
	ds_write_b64 v138, v[154:155] offset:40992
	ds_read_b128 v[154:157], v141
	v_sub_f32_e32 v169, v15, v150
	v_sub_f32_e32 v170, v14, v151
	v_add_u32_e32 v150, 48, v138
	v_sub_f32_e32 v171, v13, v152
	s_waitcnt lgkmcnt(0)
	v_pk_add_f32 v[158:159], v[10:11], v[154:155]
	v_sub_f32_e32 v172, v12, v153
	v_cndmask_b32_e64 v158, v169, v158, s[54:55]
	v_mul_f32_e32 v158, 0x3fb8aa3b, v158
	v_exp_f32_e32 v158, v158
	ds_read2st64_b64 v[150:153], v150 offset0:15 offset1:81
	v_cndmask_b32_e64 v159, v170, v159, s[54:55]
	v_mul_f32_e32 v159, 0x3fb8aa3b, v159
	v_rcp_f32_e32 v173, v158
	v_exp_f32_e32 v159, v159
	v_mul_f32_e32 v167, v1, v160
	v_mul_f32_e32 v168, v2, v161
	v_pk_add_f32 v[160:161], v[8:9], v[156:157]
	s_waitcnt lgkmcnt(0)
	v_lshlrev_b32_e32 v169, 16, v150
	v_cndmask_b32_e64 v160, v171, v160, s[54:55]
	v_lshlrev_b32_e32 v171, 16, v152
	v_mul_f32_e32 v158, v158, v169
	v_mul_f32_e32 v169, v173, v171
	v_rcp_f32_e32 v171, v159
	v_cndmask_b32_e64 v161, v172, v161, s[54:55]
	v_and_b32_e32 v150, 0xffff0000, v150
	v_and_b32_e32 v152, 0xffff0000, v152
	v_mul_f32_e32 v150, v159, v150
	v_mul_f32_e32 v159, 0x3fb8aa3b, v160
	v_mul_f32_e32 v160, v171, v152
	v_mul_f32_e32 v152, 0x3fb8aa3b, v161
	v_exp_f32_e32 v159, v159
	v_exp_f32_e32 v152, v152
	v_lshlrev_b32_e32 v170, 16, v151
	v_and_b32_e32 v151, 0xffff0000, v151
	v_rcp_f32_e32 v161, v159
	v_mul_f32_e32 v159, v159, v170
	v_rcp_f32_e32 v170, v152
	v_mul_f32_e32 v151, v152, v151
	v_mul_f32_e32 v150, 0x3d800000, v150
	v_mul_f32_e32 v151, 0x3d800000, v151
	v_lshlrev_b32_e32 v172, 16, v153
	v_and_b32_e32 v153, 0xffff0000, v153
	v_mul_f32_e32 v158, 0x3d800000, v158
	v_mul_f32_e32 v159, 0x3d800000, v159
	v_cvt_pk_bf16_f32 v150, v158, v150
	v_cvt_pk_bf16_f32 v151, v159, v151
	v_mul_f32_e32 v161, v161, v172
	v_mul_f32_e32 v170, v170, v153
	ds_write_b64 v138, v[150:151] offset:7728
	v_cvt_pk_bf16_f32 v150, v169, v160
	v_cvt_pk_bf16_f32 v151, v161, v170
	ds_write_b64 v138, v[150:151] offset:41520
	ds_read_b128 v[150:153], v142
	v_sub_f32_e32 v173, v15, v154
	v_sub_f32_e32 v174, v14, v155
	v_add_u32_e32 v154, 64, v138
	v_sub_f32_e32 v175, v13, v156
	s_waitcnt lgkmcnt(0)
	v_pk_add_f32 v[158:159], v[10:11], v[150:151]
	v_sub_f32_e32 v176, v12, v157
	v_cndmask_b32_e64 v158, v173, v158, s[54:55]
	v_mul_f32_e32 v158, 0x3fb8aa3b, v158
	v_exp_f32_e32 v158, v158
	ds_read2st64_b64 v[154:157], v154 offset0:16 offset1:82
	v_cndmask_b32_e64 v159, v174, v159, s[54:55]
	v_mul_f32_e32 v159, 0x3fb8aa3b, v159
	v_rcp_f32_e32 v177, v158
	v_exp_f32_e32 v159, v159
	v_mul_f32_e32 v171, v1, v160
	v_mul_f32_e32 v172, v2, v161
	v_pk_add_f32 v[160:161], v[8:9], v[152:153]
	s_waitcnt lgkmcnt(0)
	v_lshlrev_b32_e32 v173, 16, v154
	v_cndmask_b32_e64 v160, v175, v160, s[54:55]
	v_lshlrev_b32_e32 v175, 16, v156
	v_mul_f32_e32 v158, v158, v173
	v_mul_f32_e32 v173, v177, v175
	v_rcp_f32_e32 v175, v159
	v_cndmask_b32_e64 v161, v176, v161, s[54:55]
	v_and_b32_e32 v154, 0xffff0000, v154
	v_and_b32_e32 v156, 0xffff0000, v156
	v_mul_f32_e32 v154, v159, v154
	v_mul_f32_e32 v159, 0x3fb8aa3b, v160
	v_mul_f32_e32 v160, v175, v156
	v_mul_f32_e32 v156, 0x3fb8aa3b, v161
	v_exp_f32_e32 v159, v159
	v_exp_f32_e32 v156, v156
	v_lshlrev_b32_e32 v174, 16, v155
	v_and_b32_e32 v155, 0xffff0000, v155
	v_rcp_f32_e32 v161, v159
	v_mul_f32_e32 v159, v159, v174
	v_rcp_f32_e32 v174, v156
	v_mul_f32_e32 v155, v156, v155
	v_mul_f32_e32 v154, 0x3d800000, v154
	v_mul_f32_e32 v155, 0x3d800000, v155
	v_lshlrev_b32_e32 v176, 16, v157
	v_and_b32_e32 v157, 0xffff0000, v157
	v_mul_f32_e32 v158, 0x3d800000, v158
	v_mul_f32_e32 v159, 0x3d800000, v159
	v_cvt_pk_bf16_f32 v154, v158, v154
	v_cvt_pk_bf16_f32 v155, v159, v155
	v_mul_f32_e32 v161, v161, v176
	v_mul_f32_e32 v174, v174, v157
	ds_write_b64 v138, v[154:155] offset:8256
	v_cvt_pk_bf16_f32 v154, v173, v160
	v_cvt_pk_bf16_f32 v155, v161, v174
	ds_write_b64 v138, v[154:155] offset:42048
	ds_read_b128 v[154:157], v143
	v_sub_f32_e32 v177, v15, v150
	v_sub_f32_e32 v178, v14, v151
	v_add_u32_e32 v150, 0x50, v138
	v_sub_f32_e32 v179, v13, v152
	s_waitcnt lgkmcnt(0)
	v_pk_add_f32 v[158:159], v[10:11], v[154:155]
	v_sub_f32_e32 v180, v12, v153
	v_cndmask_b32_e64 v158, v177, v158, s[54:55]
	v_mul_f32_e32 v158, 0x3fb8aa3b, v158
	v_exp_f32_e32 v158, v158
	ds_read2st64_b64 v[150:153], v150 offset0:17 offset1:83
	v_cndmask_b32_e64 v159, v178, v159, s[54:55]
	v_mul_f32_e32 v159, 0x3fb8aa3b, v159
	v_rcp_f32_e32 v181, v158
	v_exp_f32_e32 v159, v159
	v_mul_f32_e32 v175, v1, v160
	v_mul_f32_e32 v176, v2, v161
	v_pk_add_f32 v[160:161], v[8:9], v[156:157]
	s_waitcnt lgkmcnt(0)
; __device__ __forceinline__ unsigned cvt_pk_bf16(float lo, float hi) { unsigned r; asm volatile("v_cvt_pk_bf16_f32 %0, %1, %2" : "=v"(r) : "v"(lo), "v"(hi)); return r; }
; #define LAS __attribute__((address_space(3)))
; __device__ __forceinline__ void gla_prep_phase(const Ctx& c, int j, LAS unsigned char* lds) {
;     ...
;             for (int e = 0; e < 8; ++e) { const int i = i0 + e;
;                 const f32x4 incl = *(const LAS f32x4*)(CUM + i * 256 + dq);
;                 const f32x4 cum = (dir == 0) ? (off0 + incl) : (sbase - prev); prev = incl;
;                 const u32x2 qw = *(const LAS u32x2*)(QL + i * 528 + dq * 2), kw = *(const LAS u32x2*)(KL + i * 528 + dq * 2);
;                 const float qv[4] = {__uint_as_float(qw.x << 16), __uint_as_float(qw.x & 0xffff0000u), __uint_as_float(qw.y << 16), __uint_as_float(qw.y & 0xffff0000u)};
;                 const float kv[4] = {__uint_as_float(kw.x << 16), __uint_as_float(kw.x & 0xffff0000u), __uint_as_float(kw.y << 16), __uint_as_float(kw.y & 0xffff0000u)};
;                 float qd[4], ki[4];
; #pragma unroll
;                 for (int jx = 0; jx < 4; ++jx) { const float ec = __expf(cum[jx]), rc = __builtin_amdgcn_rcpf(ec);
;                     qd[jx] = qv[jx] * ec * (1.f / 16.f); ki[jx] = kv[jx] * rc; kf[jx][e] = ki[jx] * etot[jx]; }
;                 *(LAS u32x2*)(QL + i * 528 + dq * 2) = (u32x2){pg8::cvt_pk_bf16(qd[0], qd[1]), pg8::cvt_pk_bf16(qd[2], qd[3])};
;                 *(LAS u32x2*)(KL + i * 528 + dq * 2) = (u32x2){pg8::cvt_pk_bf16(ki[0], ki[1]), pg8::cvt_pk_bf16(ki[2], ki[3])}; }
;             bf16_t* kdst = KET + tile * (256 * 64) + (size_t)dq * 64 + i0;
; #pragma unroll
;             for (int jx = 0; jx < 4; ++jx)
;                 *(u32x4*)(kdst + jx * 64) = (u32x4){pg8::cvt_pk_bf16(kf[jx][0], kf[jx][1]), pg8::cvt_pk_bf16(kf[jx][2], kf[jx][3]), pg8::cvt_pk_bf16(kf[jx][4], kf[jx][5]), pg8::cvt_pk_bf16(kf[jx][6], kf[jx][7])};
;             if (i0 == 0) *(f32x4*)(DEC + tile * 256 + dq) = etot;
	v_lshlrev_b32_e32 v177, 16, v150
	v_cndmask_b32_e64 v160, v179, v160, s[54:55]
	v_lshlrev_b32_e32 v179, 16, v152
	v_mul_f32_e32 v158, v158, v177
	v_mul_f32_e32 v177, v181, v179
	v_rcp_f32_e32 v179, v159
	v_cndmask_b32_e64 v161, v180, v161, s[54:55]
	v_and_b32_e32 v150, 0xffff0000, v150
	v_and_b32_e32 v152, 0xffff0000, v152
	v_mul_f32_e32 v150, v159, v150
	v_mul_f32_e32 v159, 0x3fb8aa3b, v160
	v_mul_f32_e32 v160, v179, v152
	v_mul_f32_e32 v152, 0x3fb8aa3b, v161
	v_exp_f32_e32 v159, v159
	v_exp_f32_e32 v152, v152
	v_lshlrev_b32_e32 v178, 16, v151
	v_and_b32_e32 v151, 0xffff0000, v151
	v_rcp_f32_e32 v161, v159
	v_mul_f32_e32 v159, v159, v178
	v_rcp_f32_e32 v178, v152
	v_mul_f32_e32 v151, v152, v151
	v_mul_f32_e32 v150, 0x3d800000, v150
	v_mul_f32_e32 v151, 0x3d800000, v151
	v_lshlrev_b32_e32 v180, 16, v153
	v_and_b32_e32 v153, 0xffff0000, v153
	v_mul_f32_e32 v158, 0x3d800000, v158
	v_mul_f32_e32 v159, 0x3d800000, v159
	v_cvt_pk_bf16_f32 v150, v158, v150
	v_cvt_pk_bf16_f32 v151, v159, v151
	v_mul_f32_e32 v161, v161, v180
	v_mul_f32_e32 v178, v178, v153
	ds_write_b64 v138, v[150:151] offset:8784
	v_cvt_pk_bf16_f32 v150, v177, v160
	v_cvt_pk_bf16_f32 v151, v161, v178
	ds_write_b64 v138, v[150:151] offset:42576
	ds_read_b128 v[150:153], v144
	v_sub_f32_e32 v181, v15, v154
	v_sub_f32_e32 v182, v14, v155
	v_add_u32_e32 v154, 0x60, v138
	v_sub_f32_e32 v183, v13, v156
	s_waitcnt lgkmcnt(0)
	v_pk_add_f32 v[158:159], v[10:11], v[150:151]
	v_sub_f32_e32 v184, v12, v157
	v_cndmask_b32_e64 v158, v181, v158, s[54:55]
	v_mul_f32_e32 v158, 0x3fb8aa3b, v158
	v_exp_f32_e32 v158, v158
	ds_read2st64_b64 v[154:157], v154 offset0:18 offset1:84
	v_cndmask_b32_e64 v159, v182, v159, s[54:55]
	v_mul_f32_e32 v159, 0x3fb8aa3b, v159
	v_rcp_f32_e32 v185, v158
	v_exp_f32_e32 v159, v159
	v_mul_f32_e32 v179, v1, v160
	v_mul_f32_e32 v180, v2, v161
	v_pk_add_f32 v[160:161], v[8:9], v[152:153]
	s_waitcnt lgkmcnt(0)
	v_lshlrev_b32_e32 v181, 16, v154
	v_cndmask_b32_e64 v160, v183, v160, s[54:55]
	v_lshlrev_b32_e32 v183, 16, v156
	v_mul_f32_e32 v158, v158, v181
	v_mul_f32_e32 v181, v185, v183
	v_rcp_f32_e32 v183, v159
	v_cndmask_b32_e64 v161, v184, v161, s[54:55]
	v_and_b32_e32 v154, 0xffff0000, v154
	v_and_b32_e32 v156, 0xffff0000, v156
	v_mul_f32_e32 v154, v159, v154
	v_mul_f32_e32 v159, 0x3fb8aa3b, v160
	v_mul_f32_e32 v160, v183, v156
	v_mul_f32_e32 v156, 0x3fb8aa3b, v161
	v_exp_f32_e32 v159, v159
	v_exp_f32_e32 v156, v156
	v_lshlrev_b32_e32 v182, 16, v155
	v_and_b32_e32 v155, 0xffff0000, v155
	v_rcp_f32_e32 v161, v159
	v_mul_f32_e32 v159, v159, v182
	v_rcp_f32_e32 v182, v156
	v_mul_f32_e32 v155, v156, v155
	v_mul_f32_e32 v154, 0x3d800000, v154
	v_mul_f32_e32 v155, 0x3d800000, v155
	v_lshlrev_b32_e32 v184, 16, v157
	v_and_b32_e32 v157, 0xffff0000, v157
	v_mul_f32_e32 v158, 0x3d800000, v158
	v_mul_f32_e32 v159, 0x3d800000, v159
	v_cvt_pk_bf16_f32 v154, v158, v154
	v_cvt_pk_bf16_f32 v155, v159, v155
	v_mul_f32_e32 v161, v161, v184
	v_mul_f32_e32 v182, v182, v157
	ds_write_b64 v138, v[154:155] offset:9312
	v_cvt_pk_bf16_f32 v154, v181, v160
	v_cvt_pk_bf16_f32 v155, v161, v182
	ds_write_b64 v138, v[154:155] offset:43104
	ds_read_b128 v[154:157], v145
	v_sub_f32_e32 v15, v15, v150
	v_sub_f32_e32 v14, v14, v151
	v_sub_f32_e32 v13, v13, v152
	v_sub_f32_e32 v12, v12, v153
	s_waitcnt lgkmcnt(0)
	v_pk_add_f32 v[154:155], v[10:11], v[154:155]
	v_pk_add_f32 v[156:157], v[8:9], v[156:157]
	v_cndmask_b32_e64 v15, v15, v154, s[54:55]
	v_mul_f32_e32 v15, 0x3fb8aa3b, v15
	v_exp_f32_e32 v15, v15
	ds_read2st64_b64 v[8:11], v146 offset0:12 offset1:78
	v_cndmask_b32_e64 v14, v14, v155, s[54:55]
	v_mul_f32_e32 v14, 0x3fb8aa3b, v14
	v_rcp_f32_e32 v154, v15
	v_exp_f32_e32 v14, v14
	v_cndmask_b32_e64 v13, v13, v156, s[54:55]
	s_waitcnt lgkmcnt(0)
	v_lshlrev_b32_e32 v150, 16, v8
	v_lshlrev_b32_e32 v152, 16, v10
	v_mul_f32_e32 v13, 0x3fb8aa3b, v13
	v_mul_f32_e32 v15, v15, v150
	v_mul_f32_e32 v150, v154, v152
	v_rcp_f32_e32 v154, v14
	v_exp_f32_e32 v13, v13
	v_cndmask_b32_e64 v12, v12, v157, s[54:55]
	v_and_b32_e32 v10, 0xffff0000, v10
	v_mul_f32_e32 v12, 0x3fb8aa3b, v12
	v_mul_f32_e32 v10, v154, v10
	v_rcp_f32_e32 v154, v13
	v_exp_f32_e32 v12, v12
	v_lshlrev_b32_e32 v151, 16, v9
	v_lshlrev_b32_e32 v153, 16, v11
	v_and_b32_e32 v8, 0xffff0000, v8
	v_and_b32_e32 v9, 0xffff0000, v9
	v_mul_f32_e32 v13, v13, v151
	v_mul_f32_e32 v151, v154, v153
	v_rcp_f32_e32 v153, v12
	v_mul_f32_e32 v8, v14, v8
	v_mul_f32_e32 v9, v12, v9
	v_mul_f32_e32 v8, 0x3d800000, v8
	v_mul_f32_e32 v9, 0x3d800000, v9
	v_and_b32_e32 v11, 0xffff0000, v11
	v_mul_f32_e32 v15, 0x3d800000, v15
	v_mul_f32_e32 v13, 0x3d800000, v13
	v_cvt_pk_bf16_f32 v8, v15, v8
	v_cvt_pk_bf16_f32 v9, v13, v9
	s_lshl_b64 s[0:1], s[66:67], 15
	v_mul_f32_e32 v6, v1, v6
	v_mul_f32_e32 v11, v153, v11
	ds_write_b64 v146, v[8:9] offset:6144
	v_cvt_pk_bf16_f32 v8, v150, v10
	v_cvt_pk_bf16_f32 v9, v151, v11
	v_lshl_add_u64 v[12:13], v[92:93], 0, s[0:1]
	v_mul_f32_e32 v162, v0, v162
	v_mul_f32_e32 v169, v0, v169
	v_mul_f32_e32 v173, v0, v173
	v_mul_f32_e32 v177, v0, v177
	v_mul_f32_e32 v158, v0, v181
	v_mul_f32_e32 v152, v0, v150
	v_mul_f32_e32 v14, v1, v10
	v_mul_f32_e32 v153, v3, v11
	ds_write_b64 v146, v[8:9] offset:39936
	v_cvt_pk_bf16_f32 v8, v7, v163
	v_cvt_pk_bf16_f32 v9, v162, v169
	v_cvt_pk_bf16_f32 v10, v173, v177
	v_cvt_pk_bf16_f32 v11, v158, v152
	global_store_dwordx4 v[12:13], v[8:11], off
	v_cvt_pk_bf16_f32 v6, v6, v164
	v_cvt_pk_bf16_f32 v7, v167, v171
	v_mul_f32_e32 v159, v1, v160
	v_mul_f32_e32 v166, v3, v166
	v_cvt_pk_bf16_f32 v8, v175, v179
	v_cvt_pk_bf16_f32 v9, v159, v14
	global_store_dwordx4 v[12:13], v[6:9], off offset:128
	v_mul_f32_e32 v170, v3, v170
	v_mul_f32_e32 v174, v3, v174
	v_cvt_pk_bf16_f32 v6, v5, v165
	v_cvt_pk_bf16_f32 v7, v168, v172
	v_mul_f32_e32 v178, v3, v178
	v_mul_f32_e32 v160, v2, v161
	v_mul_f32_e32 v161, v3, v182
	v_mul_f32_e32 v154, v2, v151
	v_cvt_pk_bf16_f32 v8, v176, v180
	v_cvt_pk_bf16_f32 v9, v160, v154
	global_store_dwordx4 v[12:13], v[6:9], off offset:256
	v_cvt_pk_bf16_f32 v4, v4, v105
	v_cvt_pk_bf16_f32 v5, v166, v170
	s_nop 1
	v_cvt_pk_bf16_f32 v6, v174, v178
	v_cvt_pk_bf16_f32 v7, v161, v153
	global_store_dwordx4 v[12:13], v[4:7], off offset:384
	s_and_saveexec_b64 s[0:1], s[52:53]
	s_cbranch_execz .LBB0_1634
	s_lshl_b64 s[58:59], s[66:67], 10
	v_lshl_add_u64 v[4:5], v[94:95], 0, s[58:59]
	global_store_dwordx4 v[4:5], v[0:3], off

; __device__ __forceinline__ int mk_tid() { int t = (int)threadIdx.x; asm volatile("" : "+v"(t)); return t; }
; #define LAS __attribute__((address_space(3)))
; __device__ __forceinline__ void gla_scan_phase(const Ctx& c, LAS unsigned char* lds) {
;     ...
;     const int tid = c.tid, wid = c.wave, lane = c.lane, r32 = lane & 31, hi = lane >> 5;
;     for (int u = blockIdx.x; u < 256; u += c.G) {
;         const int combo = (u & 7) * 4 + ((u >> 3) >> 3), es = (u >> 3) & 7;
;         const int dir = combo >> 4, bh = combo & 15, b = bh >> 2, h = bh & 3;
;         const size_t tb = (size_t)(dir * 16 + bh) * NCH;
;         u32x4 rq[4], rk[4], rp, rv, rd = {0u, 0u, 0u, 0u};
;     ...
;         __syncthreads();
;         for (int i = tid; i < 33792 / 16; i += 512) *(LAS u32x4*)(lds + SC_ST + i * 16) = (u32x4){0u, 0u, 0u, 0u};
;         f32x16 sacc[4] = {};
;         { const int c0 = dir ? NCH - 1 : 0; SC_LOAD(c0, mk_tid()); SC_STORE(mk_tid()); SC_LOAD(dir ? NCH - 2 : 1, mk_tid()); }
;         __syncthreads();
.LBB0_1693:
	s_or_b64 exec, exec, s[2:3]
	s_waitcnt lgkmcnt(0)
	s_barrier
	s_nop 0
	s_nop 0
	s_nop 0
	s_nop 0
	s_nop 0
	s_nop 0
	s_nop 0
	s_nop 0
.LBB0_1694:
	s_cmp_lt_i32 s74, 28
	s_cselect_b64 s[0:1], -1, 0
	s_cmp_gt_i32 s75, 27
	s_cselect_b64 s[2:3], -1, 0
	s_and_b64 s[0:1], s[0:1], s[2:3]
	s_andn2_b64 vcc, exec, s[0:1]
	s_cbranch_vccnz .LBB0_1810
	v_mov_b32_e32 v1, v200
	s_cmpk_gt_i32 s76, 0xff
	v_readfirstlane_b32 s0, v1
	s_cbranch_scc1 .LBB0_1756
	v_readlane_b32 s4, v254, 30
	v_readlane_b32 s5, v254, 31
	v_readlane_b32 s6, v254, 32
	v_readlane_b32 s7, v254, 33
	v_readlane_b32 s8, v254, 34
	v_readlane_b32 s9, v254, 35
	v_readlane_b32 s10, v254, 36
	v_readlane_b32 s11, v254, 37
	s_mov_b64 s[4:5], s[8:9]
	s_add_u32 s16, s4, 0x6300000
	s_addc_u32 s17, s5, 0
	s_add_u32 s33, s4, 0x2200000
	s_addc_u32 s64, s5, 0
	s_add_u32 s65, s4, 0x12500000
	s_addc_u32 s66, s5, 0
	s_add_u32 s67, s4, 0x16600000
	s_addc_u32 s68, s5, 0
	s_add_u32 s69, s4, 0x1a700000
	s_addc_u32 s76, s5, 0
	s_add_u32 s77, s4, 0x1b800000
	s_addc_u32 s78, s5, 0
	s_ashr_i32 s0, s0, 6
	s_cmp_lt_i32 s0, 4
	s_movk_i32 s1, 0x840
	s_cselect_b64 s[18:19], -1, 0
	s_cmp_gt_i32 s0, 3
	v_and_b32_e32 v2, 31, v1
	v_bfe_u32 v3, v1, 5, 1
	v_cmp_gt_i32_e64 s[2:3], s1, v1
	s_cselect_b64 s[20:21], -1, 0
	s_add_i32 s1, s0, -4
	s_lshl_b32 s22, s1, 8
	v_lshlrev_b32_e32 v196, 4, v3
	s_add_i32 s4, 0, 0x1e000
	v_lshl_or_b32 v0, s1, 6, v2
	s_lshl_b32 s1, s0, 5
	s_lshl_b32 s83, s0, 7
	v_add_u32_e32 v4, s4, v196
	s_add_i32 s80, 0, 0x13800
	s_and_b32 s1, s1, 32
	s_lshl_b32 s4, s0, 4
	s_add_i32 s82, 0, 0x11400
	s_add_i32 s26, 0, 0x15c00
	s_add_i32 s84, s83, 0xfffffe00
	s_add_i32 s85, s83, 0xfffffe40
	s_bitcmp1_b32 s0, 0
	s_movk_i32 s79, 0x90
	s_movk_i32 s5, 0xffe0
	v_mov_b32_e32 v8, s4
	s_cselect_b64 s[24:25], -1, 0
	s_lshr_b32 s0, s0, 1
	v_mul_lo_u32 v0, v0, s79
	v_or_b32_e32 v7, s1, v2
	s_movk_i32 s81, 0x210
	v_bfi_b32 v198, s5, v8, v1
	v_mov_b32_e32 v8, s82
	s_mulk_i32 s0, 0x4200
	v_add_u32_e32 v5, 0, v0
	v_mov_b32_e32 v0, s80
	v_mad_u32_u24 v197, v7, s81, 0
	v_mad_u32_u24 v7, v7, s79, v8
	v_mul_lo_u32 v8, v198, s79
	s_add_i32 s0, s0, 0
	s_mov_b64 s[6:7], s[10:11]
	v_mad_u32_u24 v6, v2, s79, v0
	v_mov_b32_e32 v0, 0
	v_add_u32_e32 v8, s80, v8
	v_lshlrev_b32_e32 v9, 3, v3
	v_lshl_or_b32 v199, v3, 2, s1
	v_mul_u32_u24_e32 v3, 0x210, v2
	v_add_u32_e32 v202, 0xfffffe00, v1
	v_lshl_add_u32 v203, v1, 4, s26
	v_mov_b32_e32 v1, s0
	s_mov_b32 s23, 0
	v_add3_u32 v201, s26, v9, v3
	v_cmp_lt_u32_e64 s[4:5], 30, v199
	v_cmp_lt_u32_e64 s[6:7], 29, v199
	v_cmp_lt_u32_e64 s[8:9], 28, v199
	v_cmp_lt_u32_e64 s[10:11], 22, v199
	v_cmp_lt_u32_e64 s[12:13], 21, v199
	v_cmp_lt_u32_e64 s[14:15], 20, v199
	v_mad_u32_u24 v204, v2, s81, v1
	s_waitcnt vmcnt(0)
	v_mov_b32_e32 v144, 0
	v_mov_b32_e32 v145, v0
	v_mov_b32_e32 v146, v0
	v_mov_b32_e32 v147, v0
	s_mov_b64 s[26:27], 0x2000
	s_mov_b64 s[28:29], 0x4000
	s_mov_b64 s[30:31], 0x6000
	s_movk_i32 s86, 0x3040
	v_add_u32_e32 v205, s22, v4
	v_add_u32_e32 v206, v5, v196
	v_add_u32_e32 v207, v6, v196
	v_add_u32_e32 v208, v7, v196
	v_add_u32_e32 v209, v8, v196
	v_readlane_b32 s87, v254, 38
	s_branch .LBB0_1698
